# scan loop: dropped redundant producer s_nops (C-interleave covers hazards), y-ring reduce fillers reordered
# baseline (speedup 1.0000x reference)
; DI float red16(float x) { x = red8(x); x += dppf<0x140>(x); return x; }
; DI void unpack4(u32x2 v, float* f) { f[0] = bflo(v[0]); f[1] = bfhi(v[0]); f[2] = bflo(v[1]); f[3] = bfhi(v[1]); }
; DI void scan_task(const Params& p, int l, int b, int h, int dir, int half, char* lds) {
;     ...
;     for (int sec = 0; sec < 3; ++sec) {
;       float pc[4], pp[4], pn[4];
;       unpack4(ld[sec][1], pc); unpack4(ld[sec][0], pp); unpack4(ld[sec][2], pn);
; #pragma unroll
;       for (int j = 0; j < 4; ++j) ts[sec][j] = pc[j] + mu0[sec][j] * (pp[j] * mprev - pc[j]) + mu1[sec][j] * (pn[j] * mnext - pc[j]);
;     }
;     ...
;       for (int ii = 0; ii < 16; ++ii) {
;         f32x4 nw = cw, nkk = ckk, nbb = cbb, nkd = ckd, nrr = crr; f32x2 nvv = cvv;
;         if (ii < 15) {
;           ps += inc; pv += inc;
;           nw = *(const f32x4*)(ps + VW * CP); nkk = *(const f32x4*)(ps + VKK * CP); nbb = *(const f32x4*)(ps + VB * CP);
;           nkd = *(const f32x4*)(ps + VKD * CP); nrr = *(const f32x4*)(ps + VR * CP); nvv = *(const f32x2*)pv;
;         }
;         __builtin_amdgcn_sched_barrier(0x7);
;         const f32x2 kk0 = {ckk[0], ckk[1]}, kk1 = {ckk[2], ckk[3]}, w0 = {cw[0], cw[1]}, w1 = {cw[2], cw[3]};
;         const f32x2 b0 = {cbb[0], cbb[1]}, b1 = {cbb[2], cbb[3]}, kd0 = {ckd[0], ckd[1]}, kd1 = {ckd[2], ckd[3]};
;         const f32x2 r0 = {crr[0], crr[1]}, r1 = {crr[2], crr[3]};
;         const f32x2 p0 = S0[0] * kk0 + S0[1] * kk1, p1 = S1[0] * kk0 + S1[1] * kk1;
;         const f32x2 u00 = S0[0] * w0 + kd0 * cvv[0], u01 = S0[1] * w1 + kd1 * cvv[0];
;         const f32x2 u10 = S1[0] * w0 + kd0 * cvv[1], u11 = S1[1] * w1 + kd1 * cvv[1];
;         const float q0 = red16(p0[0] + p0[1]), q1 = red16(p1[0] + p1[1]);
;         S0[0] = u00 - b0 * q0; S0[1] = u01 - b1 * q0;
;         S1[0] = u10 - b0 * q1; S1[1] = u11 - b1 * q1;
;         const f32x2 y0 = S0[0] * r0 + S0[1] * r1, y1 = S1[0] * r0 + S1[1] * r1;
;         *(f32x2*)py = (f32x2){y0[0] + y0[1], y1[0] + y1[1]};
;         py += dir ? -512 : 512;
;         cw = nw; ckk = nkk; cbb = nbb; ckd = nkd; crr = nrr; cvv = nvv;
;       }
.Lscan_loop:
	s_add_i32 s20, s38, 2
	s_min_u32 s20, s20, 0x8f
	s_lshl_b32 s21, s20, 4
	s_cmp_lt_u32 s20, 16
	s_movk_i32 s28, 0x9f0
	s_cselect_b32 s28, 0xf0, s28
	s_sub_u32 s28, s28, s21
	s_cmp_eq_u32 s26, 0
	s_cselect_b32 s28, s21, s28
	ds_read_b128 v[226:229], v244 offset:4624
	s_waitcnt vmcnt(8)
	ds_read_b128 v[222:225], v244 offset:272
	ds_read_b128 v[234:237], v244 offset:13328
	v_lshlrev_b32_e32 v202, 16, v78
	ds_read_b128 v[230:233], v244 offset:8976
	ds_read_b128 v[238:241], v244 offset:17680
	ds_read_b64 v[242:243], v245 offset:22032
	v_and_b32_e32 v203, 0xffff0000, v78
	v_pk_mul_f32 v[128:129], v[116:117], v[164:165]
	v_pk_mul_f32 v[130:131], v[120:121], v[164:165]
	v_lshlrev_b32_e32 v204, 16, v80
	v_pk_fma_f32 v[128:129], v[118:119], v[166:167], v[128:129]
	v_pk_fma_f32 v[130:131], v[122:123], v[166:167], v[130:131]
	v_pk_mul_f32 v[136:137], v[172:173], v[180:181] op_sel_hi:[1,0]
	v_and_b32_e32 v205, 0xffff0000, v80
	v_pk_mul_f32 v[182:183], v[174:175], v[180:181] op_sel_hi:[1,0]
	v_add_f32_e32 v132, v128, v129
	v_add_f32_e32 v134, v130, v131
	v_lshlrev_b32_e32 v206, 16, v84
	v_pk_mul_f32 v[184:185], v[172:173], v[180:181] op_sel:[0,1]
	v_pk_mul_f32 v[186:187], v[174:175], v[180:181] op_sel:[0,1]
	v_add_f32_dpp v132, v132, v132 quad_perm:[1,0,3,2] row_mask:0xf bank_mask:0xf bound_ctrl:1
	v_and_b32_e32 v207, 0xffff0000, v84
	v_add_f32_dpp v134, v134, v134 quad_perm:[1,0,3,2] row_mask:0xf bank_mask:0xf bound_ctrl:1
	v_pk_fma_f32 v[136:137], v[116:117], v[160:161], v[136:137]
	v_add_f32_dpp v132, v132, v132 quad_perm:[2,3,0,1] row_mask:0xf bank_mask:0xf bound_ctrl:1
	v_pk_fma_f32 v[204:205], v[96:97], v[204:205], v[202:203] op_sel_hi:[0,1,1] neg_lo:[0,0,1] neg_hi:[0,0,1]
	v_add_f32_dpp v134, v134, v134 quad_perm:[2,3,0,1] row_mask:0xf bank_mask:0xf bound_ctrl:1
	v_pk_fma_f32 v[182:183], v[118:119], v[162:163], v[182:183]
	v_add_f32_dpp v132, v132, v132 row_half_mirror row_mask:0xf bank_mask:0xf bound_ctrl:1
	v_pk_fma_f32 v[204:205], v[22:23], v[204:205], v[202:203]
	v_add_f32_dpp v134, v134, v134 row_half_mirror row_mask:0xf bank_mask:0xf bound_ctrl:1
	v_pk_fma_f32 v[184:185], v[120:121], v[160:161], v[184:185]
	v_add_f32_dpp v132, v132, v132 row_mirror row_mask:0xf bank_mask:0xf bound_ctrl:1
	v_pk_fma_f32 v[202:203], v[98:99], v[206:207], v[202:203] op_sel_hi:[0,1,1] neg_lo:[0,0,1] neg_hi:[0,0,1]
	v_add_f32_dpp v134, v134, v134 row_mirror row_mask:0xf bank_mask:0xf bound_ctrl:1
	v_pk_fma_f32 v[186:187], v[122:123], v[162:163], v[186:187]
	v_pk_fma_f32 v[116:117], v[168:169], v[132:133], v[136:137] op_sel_hi:[1,0,1] neg_lo:[1,0,0] neg_hi:[1,0,0]
	v_pk_fma_f32 v[202:203], v[18:19], v[202:203], v[204:205]
	v_pk_fma_f32 v[118:119], v[170:171], v[132:133], v[182:183] op_sel_hi:[1,0,1] neg_lo:[1,0,0] neg_hi:[1,0,0]
	v_pk_fma_f32 v[120:121], v[168:169], v[134:135], v[184:185] op_sel_hi:[1,0,1] neg_lo:[1,0,0] neg_hi:[1,0,0]
	v_pk_fma_f32 v[122:123], v[170:171], v[134:135], v[186:187] op_sel_hi:[1,0,1] neg_lo:[1,0,0] neg_hi:[1,0,0]
	v_lshlrev_b32_e32 v204, 16, v79
	v_pk_mul_f32 v[188:189], v[116:117], v[176:177]
	v_pk_mul_f32 v[190:191], v[120:121], v[176:177]
	v_pk_fma_f32 v[188:189], v[118:119], v[178:179], v[188:189]
	v_and_b32_e32 v205, 0xffff0000, v79
	v_pk_fma_f32 v[190:191], v[122:123], v[178:179], v[190:191]
	v_add_f32_e32 v246, v188, v189
	v_add_f32_e32 v247, v190, v191
	v_lshlrev_b32_e32 v206, 16, v81
	ds_write_b64 v159, v[246:247] offset:52224
	ds_read_b128 v[164:167], v244 offset:4896
	ds_read_b128 v[160:163], v244 offset:544
	v_and_b32_e32 v207, 0xffff0000, v81
	ds_read_b128 v[172:175], v244 offset:13600
	ds_read_b128 v[168:171], v244 offset:9248
	ds_read_b128 v[176:179], v244 offset:17952
	v_lshlrev_b32_e32 v208, 16, v85
	ds_read_b64 v[180:181], v245 offset:22304
	s_waitcnt lgkmcnt(7)
	v_pk_mul_f32 v[128:129], v[116:117], v[226:227]
	v_and_b32_e32 v209, 0xffff0000, v85
	v_pk_mul_f32 v[130:131], v[120:121], v[226:227]
	v_pk_fma_f32 v[128:129], v[118:119], v[228:229], v[128:129]
	v_pk_fma_f32 v[130:131], v[122:123], v[228:229], v[130:131]
	v_pk_fma_f32 v[206:207], v[96:97], v[206:207], v[204:205] op_sel_hi:[0,1,1] neg_lo:[0,0,1] neg_hi:[0,0,1]
	v_pk_mul_f32 v[136:137], v[234:235], v[242:243] op_sel_hi:[1,0]
	v_pk_mul_f32 v[182:183], v[236:237], v[242:243] op_sel_hi:[1,0]
	v_add_f32_e32 v132, v128, v129
	v_pk_fma_f32 v[206:207], v[24:25], v[206:207], v[204:205]
	v_add_f32_e32 v134, v130, v131
	v_pk_mul_f32 v[184:185], v[234:235], v[242:243] op_sel:[0,1]
	v_pk_mul_f32 v[186:187], v[236:237], v[242:243] op_sel:[0,1]
	v_pk_fma_f32 v[204:205], v[98:99], v[208:209], v[204:205] op_sel_hi:[0,1,1] neg_lo:[0,0,1] neg_hi:[0,0,1]
	v_add_f32_dpp v132, v132, v132 quad_perm:[1,0,3,2] row_mask:0xf bank_mask:0xf bound_ctrl:1
	v_add_f32_dpp v134, v134, v134 quad_perm:[1,0,3,2] row_mask:0xf bank_mask:0xf bound_ctrl:1
	v_pk_fma_f32 v[136:137], v[116:117], v[222:223], v[136:137]
	v_pk_fma_f32 v[204:205], v[20:21], v[204:205], v[206:207]
	v_add_f32_dpp v132, v132, v132 quad_perm:[2,3,0,1] row_mask:0xf bank_mask:0xf bound_ctrl:1
	v_add_f32_dpp v134, v134, v134 quad_perm:[2,3,0,1] row_mask:0xf bank_mask:0xf bound_ctrl:1
	v_pk_fma_f32 v[182:183], v[118:119], v[224:225], v[182:183]
	v_lshlrev_b32_e32 v206, 16, v82
	v_add_f32_dpp v132, v132, v132 row_half_mirror row_mask:0xf bank_mask:0xf bound_ctrl:1
	v_add_f32_dpp v134, v134, v134 row_half_mirror row_mask:0xf bank_mask:0xf bound_ctrl:1
	v_pk_fma_f32 v[184:185], v[120:121], v[222:223], v[184:185]
	v_and_b32_e32 v207, 0xffff0000, v82
	v_add_f32_dpp v132, v132, v132 row_mirror row_mask:0xf bank_mask:0xf bound_ctrl:1
	v_add_f32_dpp v134, v134, v134 row_mirror row_mask:0xf bank_mask:0xf bound_ctrl:1
; DI float red16(float x) { x = red8(x); x += dppf<0x140>(x); return x; }
; DI void unpack4(u32x2 v, float* f) { f[0] = bflo(v[0]); f[1] = bfhi(v[0]); f[2] = bflo(v[1]); f[3] = bfhi(v[1]); }
; DI void scan_task(const Params& p, int l, int b, int h, int dir, int half, char* lds) {
;     ...
;     for (int sec = 0; sec < 3; ++sec) {
;       float pc[4], pp[4], pn[4];
;       unpack4(ld[sec][1], pc); unpack4(ld[sec][0], pp); unpack4(ld[sec][2], pn);
; #pragma unroll
;       for (int j = 0; j < 4; ++j) ts[sec][j] = pc[j] + mu0[sec][j] * (pp[j] * mprev - pc[j]) + mu1[sec][j] * (pn[j] * mnext - pc[j]);
;     }
;     ...
;         const f32x2 kk0 = {ckk[0], ckk[1]}, kk1 = {ckk[2], ckk[3]}, w0 = {cw[0], cw[1]}, w1 = {cw[2], cw[3]};
;         const f32x2 b0 = {cbb[0], cbb[1]}, b1 = {cbb[2], cbb[3]}, kd0 = {ckd[0], ckd[1]}, kd1 = {ckd[2], ckd[3]};
;         const f32x2 r0 = {crr[0], crr[1]}, r1 = {crr[2], crr[3]};
;         const f32x2 p0 = S0[0] * kk0 + S0[1] * kk1, p1 = S1[0] * kk0 + S1[1] * kk1;
;         const f32x2 u00 = S0[0] * w0 + kd0 * cvv[0], u01 = S0[1] * w1 + kd1 * cvv[0];
;         const f32x2 u10 = S1[0] * w0 + kd0 * cvv[1], u11 = S1[1] * w1 + kd1 * cvv[1];
;         const float q0 = red16(p0[0] + p0[1]), q1 = red16(p1[0] + p1[1]);
;         S0[0] = u00 - b0 * q0; S0[1] = u01 - b1 * q0;
;         S1[0] = u10 - b0 * q1; S1[1] = u11 - b1 * q1;
;         const f32x2 y0 = S0[0] * r0 + S0[1] * r1, y1 = S1[0] * r0 + S1[1] * r1;
;         *(f32x2*)py = (f32x2){y0[0] + y0[1], y1[0] + y1[1]};
;         py += dir ? -512 : 512;
;         cw = nw; ckk = nkk; cbb = nbb; ckd = nkd; crr = nrr; cvv = nvv;
;       }
	v_pk_fma_f32 v[186:187], v[122:123], v[224:225], v[186:187]
	v_lshlrev_b32_e32 v208, 16, v88
	v_pk_fma_f32 v[116:117], v[230:231], v[132:133], v[136:137] op_sel_hi:[1,0,1] neg_lo:[1,0,0] neg_hi:[1,0,0]
	v_pk_fma_f32 v[118:119], v[232:233], v[132:133], v[182:183] op_sel_hi:[1,0,1] neg_lo:[1,0,0] neg_hi:[1,0,0]
	v_pk_fma_f32 v[120:121], v[230:231], v[134:135], v[184:185] op_sel_hi:[1,0,1] neg_lo:[1,0,0] neg_hi:[1,0,0]
	v_and_b32_e32 v209, 0xffff0000, v88
	v_pk_fma_f32 v[122:123], v[232:233], v[134:135], v[186:187] op_sel_hi:[1,0,1] neg_lo:[1,0,0] neg_hi:[1,0,0]
	v_pk_mul_f32 v[188:189], v[116:117], v[238:239]
	v_pk_mul_f32 v[190:191], v[120:121], v[238:239]
	v_lshlrev_b32_e32 v210, 16, v90
	v_pk_fma_f32 v[188:189], v[118:119], v[240:241], v[188:189]
	v_pk_fma_f32 v[190:191], v[122:123], v[240:241], v[190:191]
	v_and_b32_e32 v211, 0xffff0000, v90
	v_add_f32_e32 v246, v188, v189
	v_add_f32_e32 v247, v190, v191
	ds_write_b64 v159, v[246:247] offset:54272
	v_pk_fma_f32 v[208:209], v[96:97], v[208:209], v[206:207] op_sel_hi:[0,1,1] neg_lo:[0,0,1] neg_hi:[0,0,1]
	ds_read_b128 v[226:229], v244 offset:5168
	ds_read_b128 v[222:225], v244 offset:816
	ds_read_b128 v[234:237], v244 offset:13872
	v_pk_fma_f32 v[208:209], v[26:27], v[208:209], v[206:207]
	ds_read_b128 v[230:233], v244 offset:9520
	ds_read_b128 v[238:241], v244 offset:18224
	ds_read_b64 v[242:243], v245 offset:22576
	v_pk_fma_f32 v[206:207], v[98:99], v[210:211], v[206:207] op_sel_hi:[0,1,1] neg_lo:[0,0,1] neg_hi:[0,0,1]
	s_waitcnt lgkmcnt(7)
	v_pk_mul_f32 v[128:129], v[116:117], v[164:165]
	v_pk_mul_f32 v[130:131], v[120:121], v[164:165]
	v_pk_fma_f32 v[206:207], v[30:31], v[206:207], v[208:209]
	v_pk_fma_f32 v[128:129], v[118:119], v[166:167], v[128:129]
	v_pk_fma_f32 v[130:131], v[122:123], v[166:167], v[130:131]
	v_pk_mul_f32 v[136:137], v[172:173], v[180:181] op_sel_hi:[1,0]
	v_lshlrev_b32_e32 v208, 16, v83
	v_pk_mul_f32 v[182:183], v[174:175], v[180:181] op_sel_hi:[1,0]
	v_add_f32_e32 v132, v128, v129
	v_add_f32_e32 v134, v130, v131
	v_and_b32_e32 v209, 0xffff0000, v83
	v_pk_mul_f32 v[184:185], v[172:173], v[180:181] op_sel:[0,1]
	v_pk_mul_f32 v[186:187], v[174:175], v[180:181] op_sel:[0,1]
	v_add_f32_dpp v132, v132, v132 quad_perm:[1,0,3,2] row_mask:0xf bank_mask:0xf bound_ctrl:1
	v_lshlrev_b32_e32 v210, 16, v89
	v_add_f32_dpp v134, v134, v134 quad_perm:[1,0,3,2] row_mask:0xf bank_mask:0xf bound_ctrl:1
	v_pk_fma_f32 v[136:137], v[116:117], v[160:161], v[136:137]
	v_add_f32_dpp v132, v132, v132 quad_perm:[2,3,0,1] row_mask:0xf bank_mask:0xf bound_ctrl:1
	v_and_b32_e32 v211, 0xffff0000, v89
	v_add_f32_dpp v134, v134, v134 quad_perm:[2,3,0,1] row_mask:0xf bank_mask:0xf bound_ctrl:1
	v_pk_fma_f32 v[182:183], v[118:119], v[162:163], v[182:183]
	v_add_f32_dpp v132, v132, v132 row_half_mirror row_mask:0xf bank_mask:0xf bound_ctrl:1
	v_lshlrev_b32_e32 v212, 16, v91
	v_add_f32_dpp v134, v134, v134 row_half_mirror row_mask:0xf bank_mask:0xf bound_ctrl:1
	v_pk_fma_f32 v[184:185], v[120:121], v[160:161], v[184:185]
	v_add_f32_dpp v132, v132, v132 row_mirror row_mask:0xf bank_mask:0xf bound_ctrl:1
	v_and_b32_e32 v213, 0xffff0000, v91
	v_add_f32_dpp v134, v134, v134 row_mirror row_mask:0xf bank_mask:0xf bound_ctrl:1
	v_pk_fma_f32 v[186:187], v[122:123], v[162:163], v[186:187]
	v_pk_fma_f32 v[116:117], v[168:169], v[132:133], v[136:137] op_sel_hi:[1,0,1] neg_lo:[1,0,0] neg_hi:[1,0,0]
	v_pk_fma_f32 v[210:211], v[96:97], v[210:211], v[208:209] op_sel_hi:[0,1,1] neg_lo:[0,0,1] neg_hi:[0,0,1]
	v_pk_fma_f32 v[118:119], v[170:171], v[132:133], v[182:183] op_sel_hi:[1,0,1] neg_lo:[1,0,0] neg_hi:[1,0,0]
	v_pk_fma_f32 v[120:121], v[168:169], v[134:135], v[184:185] op_sel_hi:[1,0,1] neg_lo:[1,0,0] neg_hi:[1,0,0]
	v_pk_fma_f32 v[122:123], v[170:171], v[134:135], v[186:187] op_sel_hi:[1,0,1] neg_lo:[1,0,0] neg_hi:[1,0,0]
	v_pk_fma_f32 v[210:211], v[28:29], v[210:211], v[208:209]
	v_pk_mul_f32 v[188:189], v[116:117], v[176:177]
	v_pk_mul_f32 v[190:191], v[120:121], v[176:177]
	v_pk_fma_f32 v[188:189], v[118:119], v[178:179], v[188:189]
	v_pk_fma_f32 v[208:209], v[98:99], v[212:213], v[208:209] op_sel_hi:[0,1,1] neg_lo:[0,0,1] neg_hi:[0,0,1]
	v_pk_fma_f32 v[190:191], v[122:123], v[178:179], v[190:191]
	v_add_f32_e32 v246, v188, v189
	v_add_f32_e32 v247, v190, v191
	v_pk_fma_f32 v[208:209], v[32:33], v[208:209], v[210:211]
	ds_write_b64 v159, v[246:247] offset:56320
	ds_read_b128 v[164:167], v244 offset:5440
	ds_read_b128 v[160:163], v244 offset:1088
	v_lshlrev_b32_e32 v210, 16, v86
	ds_read_b128 v[172:175], v244 offset:14144
	ds_read_b128 v[168:171], v244 offset:9792
	ds_read_b128 v[176:179], v244 offset:18496
	v_and_b32_e32 v211, 0xffff0000, v86
	ds_read_b64 v[180:181], v245 offset:22848
	s_waitcnt lgkmcnt(7)
; DI void scan_task(const Params& p, int l, int b, int h, int dir, int half, char* lds) {
;     ...
;     *(f32x4*)(cb + VR * CP + st_p * CS + c4 * 4) = (f32x4){ts[0][0], ts[0][1], ts[0][2], ts[0][3]};
;     *(f32x4*)(cb + VV * CP + st_p * CS + c4 * 4) = (f32x4){ts[2][0], ts[2][1], ts[2][2], ts[2][3]};
;     *(f32x4*)(tk + st_p * CS + c4 * 4) = (f32x4){ts[1][0], ts[1][1], ts[1][2], ts[1][3]};
;     float kx[4], ss = 0.f;
; #pragma unroll
;     ...
;       for (int ii = 0; ii < 16; ++ii) {
;         f32x4 nw = cw, nkk = ckk, nbb = cbb, nkd = ckd, nrr = crr; f32x2 nvv = cvv;
;         if (ii < 15) {
;           ps += inc; pv += inc;
;           nw = *(const f32x4*)(ps + VW * CP); nkk = *(const f32x4*)(ps + VKK * CP); nbb = *(const f32x4*)(ps + VB * CP);
;           nkd = *(const f32x4*)(ps + VKD * CP); nrr = *(const f32x4*)(ps + VR * CP); nvv = *(const f32x2*)pv;
;         }
;         __builtin_amdgcn_sched_barrier(0x7);
;         const f32x2 kk0 = {ckk[0], ckk[1]}, kk1 = {ckk[2], ckk[3]}, w0 = {cw[0], cw[1]}, w1 = {cw[2], cw[3]};
;         const f32x2 b0 = {cbb[0], cbb[1]}, b1 = {cbb[2], cbb[3]}, kd0 = {ckd[0], ckd[1]}, kd1 = {ckd[2], ckd[3]};
;         const f32x2 r0 = {crr[0], crr[1]}, r1 = {crr[2], crr[3]};
;         const f32x2 p0 = S0[0] * kk0 + S0[1] * kk1, p1 = S1[0] * kk0 + S1[1] * kk1;
;         const f32x2 u00 = S0[0] * w0 + kd0 * cvv[0], u01 = S0[1] * w1 + kd1 * cvv[0];
;         const f32x2 u10 = S1[0] * w0 + kd0 * cvv[1], u11 = S1[1] * w1 + kd1 * cvv[1];
;         const float q0 = red16(p0[0] + p0[1]), q1 = red16(p1[0] + p1[1]);
;         S0[0] = u00 - b0 * q0; S0[1] = u01 - b1 * q0;
;         S1[0] = u10 - b0 * q1; S1[1] = u11 - b1 * q1;
;         const f32x2 y0 = S0[0] * r0 + S0[1] * r1, y1 = S1[0] * r0 + S1[1] * r1;
;         *(f32x2*)py = (f32x2){y0[0] + y0[1], y1[0] + y1[1]};
;         py += dir ? -512 : 512;
;         cw = nw; ckk = nkk; cbb = nbb; ckd = nkd; crr = nrr; cvv = nvv;
;       }
;     }
;     __syncthreads();
;     {
;       const int slo = chunk_lo(c);
;       const float* yp = ybuf + (st_p * 16 + c4) * 32;
;       f32x4 a = *(const f32x4*)(yp + 4 * (c4 & 7));
; #pragma unroll
;       for (int i = 1; i < 8; ++i) a += *(const f32x4*)(yp + 4 * ((i + c4) & 7));
;       *(f32x2*)(p.Y + (size_t)dir * T_TOK * 384 + (size_t)(b * TB + slo + st_p) * 384 + hc + half * 32 + c4 * 2) = (f32x2){a[0] + a[2], a[1] + a[3]};
	v_pk_mul_f32 v[128:129], v[116:117], v[226:227]
	v_lshlrev_b32_e32 v212, 16, v92
	v_pk_mul_f32 v[130:131], v[120:121], v[226:227]
	v_pk_fma_f32 v[128:129], v[118:119], v[228:229], v[128:129]
	v_pk_fma_f32 v[130:131], v[122:123], v[228:229], v[130:131]
	v_and_b32_e32 v213, 0xffff0000, v92
	v_pk_mul_f32 v[136:137], v[234:235], v[242:243] op_sel_hi:[1,0]
	v_pk_mul_f32 v[182:183], v[236:237], v[242:243] op_sel_hi:[1,0]
	v_add_f32_e32 v132, v128, v129
	v_lshlrev_b32_e32 v214, 16, v94
	v_add_f32_e32 v134, v130, v131
	v_pk_mul_f32 v[184:185], v[234:235], v[242:243] op_sel:[0,1]
	v_pk_mul_f32 v[186:187], v[236:237], v[242:243] op_sel:[0,1]
	v_and_b32_e32 v215, 0xffff0000, v94
	v_add_f32_dpp v132, v132, v132 quad_perm:[1,0,3,2] row_mask:0xf bank_mask:0xf bound_ctrl:1
	v_add_f32_dpp v134, v134, v134 quad_perm:[1,0,3,2] row_mask:0xf bank_mask:0xf bound_ctrl:1
	v_pk_fma_f32 v[136:137], v[116:117], v[222:223], v[136:137]
	v_pk_fma_f32 v[212:213], v[96:97], v[212:213], v[210:211] op_sel_hi:[0,1,1] neg_lo:[0,0,1] neg_hi:[0,0,1]
	v_add_f32_dpp v132, v132, v132 quad_perm:[2,3,0,1] row_mask:0xf bank_mask:0xf bound_ctrl:1
	v_add_f32_dpp v134, v134, v134 quad_perm:[2,3,0,1] row_mask:0xf bank_mask:0xf bound_ctrl:1
	v_pk_fma_f32 v[182:183], v[118:119], v[224:225], v[182:183]
	v_pk_fma_f32 v[212:213], v[38:39], v[212:213], v[210:211]
	v_add_f32_dpp v132, v132, v132 row_half_mirror row_mask:0xf bank_mask:0xf bound_ctrl:1
	v_add_f32_dpp v134, v134, v134 row_half_mirror row_mask:0xf bank_mask:0xf bound_ctrl:1
	v_pk_fma_f32 v[184:185], v[120:121], v[222:223], v[184:185]
	v_pk_fma_f32 v[210:211], v[98:99], v[214:215], v[210:211] op_sel_hi:[0,1,1] neg_lo:[0,0,1] neg_hi:[0,0,1]
	v_add_f32_dpp v132, v132, v132 row_mirror row_mask:0xf bank_mask:0xf bound_ctrl:1
	v_add_f32_dpp v134, v134, v134 row_mirror row_mask:0xf bank_mask:0xf bound_ctrl:1
	v_pk_fma_f32 v[186:187], v[122:123], v[224:225], v[186:187]
	v_pk_fma_f32 v[210:211], v[34:35], v[210:211], v[212:213]
	v_pk_fma_f32 v[116:117], v[230:231], v[132:133], v[136:137] op_sel_hi:[1,0,1] neg_lo:[1,0,0] neg_hi:[1,0,0]
	v_pk_fma_f32 v[118:119], v[232:233], v[132:133], v[182:183] op_sel_hi:[1,0,1] neg_lo:[1,0,0] neg_hi:[1,0,0]
	v_lshlrev_b32_e32 v212, 16, v87
	v_pk_fma_f32 v[120:121], v[230:231], v[134:135], v[184:185] op_sel_hi:[1,0,1] neg_lo:[1,0,0] neg_hi:[1,0,0]
	v_pk_fma_f32 v[122:123], v[232:233], v[134:135], v[186:187] op_sel_hi:[1,0,1] neg_lo:[1,0,0] neg_hi:[1,0,0]
	v_pk_mul_f32 v[188:189], v[116:117], v[238:239]
	v_and_b32_e32 v213, 0xffff0000, v87
	v_pk_mul_f32 v[190:191], v[120:121], v[238:239]
	v_pk_fma_f32 v[188:189], v[118:119], v[240:241], v[188:189]
	v_pk_fma_f32 v[190:191], v[122:123], v[240:241], v[190:191]
	v_lshlrev_b32_e32 v214, 16, v93
	v_add_f32_e32 v246, v188, v189
	v_add_f32_e32 v247, v190, v191
	ds_write_b64 v159, v[246:247] offset:58368
	v_and_b32_e32 v215, 0xffff0000, v93
	ds_read_b128 v[192:195], v124 offset:52224
	ds_read_b128 v[196:199], v124 offset:52240
	s_mul_i32 s20, s26, 15
	v_lshlrev_b32_e32 v216, 16, v95
	s_add_i32 s20, s20, 0
	s_add_i32 s20, s20, s27
	s_waitcnt lgkmcnt(0)
	v_and_b32_e32 v217, 0xffff0000, v95
	v_pk_add_f32 v[192:193], v[192:193], v[194:195]
	v_pk_add_f32 v[196:197], v[196:197], v[198:199]
	s_add_i32 s20, s20, s100
	v_pk_fma_f32 v[214:215], v[96:97], v[214:215], v[212:213] op_sel_hi:[0,1,1] neg_lo:[0,0,1] neg_hi:[0,0,1]
	v_pk_add_f32 v[192:193], v[192:193], v[196:197]
	s_mulk_i32 s20, 0x600
	s_nop 0
	v_pk_fma_f32 v[214:215], v[40:41], v[214:215], v[212:213]
	v_add_f32_dpp v192, v192, v192 quad_perm:[1,0,3,2] row_mask:0xf bank_mask:0xf bound_ctrl:1
	v_add_f32_dpp v193, v193, v193 quad_perm:[1,0,3,2] row_mask:0xf bank_mask:0xf bound_ctrl:1
	v_add_u32_e32 v125, s20, v200
	v_pk_fma_f32 v[212:213], v[98:99], v[216:217], v[212:213] op_sel_hi:[0,1,1] neg_lo:[0,0,1] neg_hi:[0,0,1]
	v_add_f32_dpp v192, v192, v192 quad_perm:[2,3,0,1] row_mask:0xf bank_mask:0xf bound_ctrl:1
	v_add_f32_dpp v193, v193, v193 quad_perm:[2,3,0,1] row_mask:0xf bank_mask:0xf bound_ctrl:1
	global_store_dwordx2 v125, v[192:193], s[98:99]
	v_pk_fma_f32 v[212:213], v[36:37], v[212:213], v[214:215]
	ds_read_b128 v[226:229], v244 offset:5712
	ds_read_b128 v[222:225], v244 offset:1360
	ds_read_b128 v[234:237], v244 offset:14416
	v_pk_mul_f32 v[214:215], v[42:43], v[206:207]
	ds_read_b128 v[230:233], v244 offset:10064
	ds_read_b128 v[238:241], v244 offset:18768
	ds_read_b64 v[242:243], v245 offset:23120
	v_pk_mul_f32 v[218:219], v[44:45], v[208:209]
	v_pk_mul_f32 v[128:129], v[116:117], v[164:165]
	v_pk_mul_f32 v[130:131], v[120:121], v[164:165]
	v_pk_mul_f32 v[216:217], v[214:215], v[214:215]
	v_pk_fma_f32 v[128:129], v[118:119], v[166:167], v[128:129]
	v_pk_fma_f32 v[130:131], v[122:123], v[166:167], v[130:131]
	v_pk_mul_f32 v[136:137], v[172:173], v[180:181] op_sel_hi:[1,0]
	v_pk_mul_f32 v[220:221], v[218:219], v[218:219]
	v_pk_mul_f32 v[182:183], v[174:175], v[180:181] op_sel_hi:[1,0]
	v_add_f32_e32 v132, v128, v129
	v_add_f32_e32 v134, v130, v131
	v_add_f32_e32 v110, v216, v217
	v_pk_mul_f32 v[184:185], v[172:173], v[180:181] op_sel:[0,1]
	v_pk_mul_f32 v[186:187], v[174:175], v[180:181] op_sel:[0,1]
	v_add_f32_dpp v132, v132, v132 quad_perm:[1,0,3,2] row_mask:0xf bank_mask:0xf bound_ctrl:1
	v_add_f32_e32 v110, v220, v110
	v_add_f32_dpp v134, v134, v134 quad_perm:[1,0,3,2] row_mask:0xf bank_mask:0xf bound_ctrl:1
	v_pk_fma_f32 v[136:137], v[116:117], v[160:161], v[136:137]
	v_add_f32_dpp v132, v132, v132 quad_perm:[2,3,0,1] row_mask:0xf bank_mask:0xf bound_ctrl:1
	v_add_f32_e32 v110, v221, v110
	v_add_f32_dpp v134, v134, v134 quad_perm:[2,3,0,1] row_mask:0xf bank_mask:0xf bound_ctrl:1
	v_pk_fma_f32 v[182:183], v[118:119], v[162:163], v[182:183]
	v_add_f32_dpp v132, v132, v132 row_half_mirror row_mask:0xf bank_mask:0xf bound_ctrl:1
	ds_write_b128 v100, v[202:205] offset:17408
	v_add_f32_dpp v134, v134, v134 row_half_mirror row_mask:0xf bank_mask:0xf bound_ctrl:1
	v_pk_fma_f32 v[184:185], v[120:121], v[160:161], v[184:185]
	v_add_f32_dpp v132, v132, v132 row_mirror row_mask:0xf bank_mask:0xf bound_ctrl:1
	ds_write_b128 v100, v[210:213] offset:21760
	v_add_f32_dpp v134, v134, v134 row_mirror row_mask:0xf bank_mask:0xf bound_ctrl:1
	v_pk_fma_f32 v[186:187], v[122:123], v[162:163], v[186:187]
	v_pk_fma_f32 v[116:117], v[168:169], v[132:133], v[136:137] op_sel_hi:[1,0,1] neg_lo:[1,0,0] neg_hi:[1,0,0]
	ds_write_b128 v100, v[206:209] offset:13056
	v_pk_fma_f32 v[118:119], v[170:171], v[132:133], v[182:183] op_sel_hi:[1,0,1] neg_lo:[1,0,0] neg_hi:[1,0,0]
	v_pk_fma_f32 v[120:121], v[168:169], v[134:135], v[184:185] op_sel_hi:[1,0,1] neg_lo:[1,0,0] neg_hi:[1,0,0]
	v_pk_fma_f32 v[122:123], v[170:171], v[134:135], v[186:187] op_sel_hi:[1,0,1] neg_lo:[1,0,0] neg_hi:[1,0,0]
	v_add_f32_dpp v110, v110, v110 quad_perm:[1,0,3,2] row_mask:0xf bank_mask:0xf bound_ctrl:1
	v_pk_mul_f32 v[188:189], v[116:117], v[176:177]
	v_pk_mul_f32 v[190:191], v[120:121], v[176:177]
	v_pk_fma_f32 v[188:189], v[118:119], v[178:179], v[188:189]
	s_waitcnt vmcnt(4)
; DI float sigmoidf_(float x) { return __builtin_amdgcn_rcpf(1.f + __expf(-x)); }
; DI void scan_task(const Params& p, int l, int b, int h, int dir, int half, char* lds) {
;     ...
;   auto issue_loads = [&](int c) {
;     const int slo = chunk_lo(c);
;     const int s = slo + st_p;
;     const bool hasprev = (s != 0 && s != NCTX), hasnext = (s != NCTX - 1 && s != TB - 1);
;     const bf16_t* pa = p.PA + (size_t)(b * TB + s) * LDPA + hc + c4 * 4;
;     const int op = hasprev ? -LDPA : 0, on = hasnext ? LDPA : 0;
;     mprev = hasprev ? 1.f : 0.f; mnext = hasnext ? 1.f : 0.f;
; #pragma unroll
;     for (int sec = 0; sec < 3; ++sec) {
;       ld[sec][1] = *(const u32x2*)(pa + sec * 384);
;       ld[sec][0] = *(const u32x2*)(pa + sec * 384 + op);
;       ld[sec][2] = *(const u32x2*)(pa + sec * 384 + on);
;     }
;     const size_t trow = (size_t)(b * TB + slo + fr) * 64;
; #pragma unroll
;     for (int ks = 0; ks < 2; ++ks) { aw[ks] = *(const bf16x8*)(p.TW + trow + ks * 32 + fq * 8); aa[ks] = *(const bf16x8*)(p.TA + trow + ks * 32 + fq * 8); }
;     ...
;     const float inv = rsqrtf(ss + 1e-12f);
;     *(f32x4*)(cb + VKK * CP + st_p * CS + c4 * 4) = (f32x4){kx[0] * inv, kx[1] * inv, kx[2] * inv, kx[3] * inv};
;     __syncthreads();
;     f32x4 dw = {0.f, 0.f, 0.f, 0.f}, da = {0.f, 0.f, 0.f, 0.f};
; #pragma unroll
;     for (int ks = 0; ks < 2; ++ks) {
;       dw = __builtin_amdgcn_mfma_f32_16x16x32_bf16(bw[ks], aw[ks], dw, 0, 0, 0);
;       da = __builtin_amdgcn_mfma_f32_16x16x32_bf16(ba[ks], aa[ks], da, 0, 0, 0);
;     }
;     {
;       const f32x4 kv = *(const f32x4*)(tk + fr * CS + colB);
;       const f32x4 kkv = *(const f32x4*)(cb + VKK * CP + fr * CS + colB);
;       f32x4 wv, kdv, bv;
; #pragma unroll
;       for (int j = 0; j < 4; ++j) {
;         wv[j] = __expf(-LOG_DECAY_SCALE * sigmoidf_(w0[j] + dw[j]));
	v_pk_fma_f32 v[190:191], v[122:123], v[178:179], v[190:191]
	v_add_f32_e32 v246, v188, v189
	v_add_f32_e32 v247, v190, v191
	v_mfma_f32_16x16x32_bf16 v[206:209], v[2:5], v[62:65], 0
	ds_write_b64 v159, v[246:247] offset:52224
	ds_read_b128 v[164:167], v244 offset:5984
	ds_read_b128 v[160:163], v244 offset:1632
	v_add_f32_dpp v110, v110, v110 quad_perm:[2,3,0,1] row_mask:0xf bank_mask:0xf bound_ctrl:1
	ds_read_b128 v[172:175], v244 offset:14688
	ds_read_b128 v[168:171], v244 offset:10336
	ds_read_b128 v[176:179], v244 offset:19040
	v_add_f32_dpp v110, v110, v110 row_half_mirror row_mask:0xf bank_mask:0xf bound_ctrl:1
	ds_read_b64 v[180:181], v245 offset:23392
	s_waitcnt lgkmcnt(10)
	v_pk_mul_f32 v[128:129], v[116:117], v[226:227]
	v_add_f32_dpp v110, v110, v110 row_mirror row_mask:0xf bank_mask:0xf bound_ctrl:1
	v_pk_mul_f32 v[130:131], v[120:121], v[226:227]
	v_pk_fma_f32 v[128:129], v[118:119], v[228:229], v[128:129]
	v_add_f32_e32 v110, 0x2b8cbccc, v110
	v_pk_fma_f32 v[130:131], v[122:123], v[228:229], v[130:131]
	v_pk_mul_f32 v[136:137], v[234:235], v[242:243] op_sel_hi:[1,0]
	v_pk_mul_f32 v[182:183], v[236:237], v[242:243] op_sel_hi:[1,0]
	v_mul_f32_e32 v201, 0x4b800000, v110
	v_add_f32_e32 v132, v128, v129
	v_add_f32_e32 v134, v130, v131
	v_pk_mul_f32 v[184:185], v[234:235], v[242:243] op_sel:[0,1]
	v_cmp_gt_f32_e32 vcc, s53, v110
	v_pk_mul_f32 v[186:187], v[236:237], v[242:243] op_sel:[0,1]
	v_add_f32_dpp v132, v132, v132 quad_perm:[1,0,3,2] row_mask:0xf bank_mask:0xf bound_ctrl:1
	v_add_f32_dpp v134, v134, v134 quad_perm:[1,0,3,2] row_mask:0xf bank_mask:0xf bound_ctrl:1
	v_cndmask_b32_e32 v110, v110, v201, vcc
	v_pk_fma_f32 v[136:137], v[116:117], v[222:223], v[136:137]
	v_add_f32_dpp v132, v132, v132 quad_perm:[2,3,0,1] row_mask:0xf bank_mask:0xf bound_ctrl:1
	v_add_f32_dpp v134, v134, v134 quad_perm:[2,3,0,1] row_mask:0xf bank_mask:0xf bound_ctrl:1
	v_rsq_f32_e32 v110, v110
	v_pk_fma_f32 v[182:183], v[118:119], v[224:225], v[182:183]
	v_add_f32_dpp v132, v132, v132 row_half_mirror row_mask:0xf bank_mask:0xf bound_ctrl:1
	v_add_f32_dpp v134, v134, v134 row_half_mirror row_mask:0xf bank_mask:0xf bound_ctrl:1
	v_mul_f32_e32 v201, 0x45800000, v110
	v_pk_fma_f32 v[184:185], v[120:121], v[222:223], v[184:185]
	v_add_f32_dpp v132, v132, v132 row_mirror row_mask:0xf bank_mask:0xf bound_ctrl:1
	v_add_f32_dpp v134, v134, v134 row_mirror row_mask:0xf bank_mask:0xf bound_ctrl:1
	v_cndmask_b32_e32 v110, v110, v201, vcc
	v_pk_fma_f32 v[186:187], v[122:123], v[224:225], v[186:187]
	v_pk_fma_f32 v[116:117], v[230:231], v[132:133], v[136:137] op_sel_hi:[1,0,1] neg_lo:[1,0,0] neg_hi:[1,0,0]
	v_pk_fma_f32 v[118:119], v[232:233], v[132:133], v[182:183] op_sel_hi:[1,0,1] neg_lo:[1,0,0] neg_hi:[1,0,0]
	v_pk_mul_f32 v[204:205], v[218:219], v[110:111] op_sel_hi:[1,0]
	v_pk_fma_f32 v[120:121], v[230:231], v[134:135], v[184:185] op_sel_hi:[1,0,1] neg_lo:[1,0,0] neg_hi:[1,0,0]
	v_pk_fma_f32 v[122:123], v[232:233], v[134:135], v[186:187] op_sel_hi:[1,0,1] neg_lo:[1,0,0] neg_hi:[1,0,0]
	v_pk_mul_f32 v[188:189], v[116:117], v[238:239]
	v_pk_mul_f32 v[202:203], v[214:215], v[110:111] op_sel_hi:[1,0]
	v_pk_mul_f32 v[190:191], v[120:121], v[238:239]
	v_pk_fma_f32 v[188:189], v[118:119], v[240:241], v[188:189]
	v_pk_fma_f32 v[190:191], v[122:123], v[240:241], v[190:191]
	ds_write_b128 v100, v[202:205] offset:4352
	v_add_f32_e32 v246, v188, v189
	v_add_f32_e32 v247, v190, v191
	ds_write_b64 v159, v[246:247] offset:54272
	v_mfma_f32_16x16x32_bf16 v[202:205], v[6:9], v[66:69], v[206:209]
	ds_read_b128 v[226:229], v244 offset:6256
	ds_read_b128 v[222:225], v244 offset:1904
	ds_read_b128 v[234:237], v244 offset:14960
	s_waitcnt lgkmcnt(0)
	s_barrier
	ds_read_b128 v[230:233], v244 offset:10608
	ds_read_b128 v[238:241], v244 offset:19312
	ds_read_b64 v[242:243], v245 offset:23664
	v_mfma_f32_16x16x32_bf16 v[206:209], v[10:13], v[70:73], 0
	v_pk_mul_f32 v[128:129], v[116:117], v[164:165]
	v_pk_mul_f32 v[130:131], v[120:121], v[164:165]
	ds_read_b128 v[210:213], v97 offset:13056
	v_pk_fma_f32 v[128:129], v[118:119], v[166:167], v[128:129]
	v_pk_fma_f32 v[130:131], v[122:123], v[166:167], v[130:131]
	v_pk_mul_f32 v[136:137], v[172:173], v[180:181] op_sel_hi:[1,0]
	ds_read_b128 v[214:217], v97 offset:4352
	v_pk_mul_f32 v[182:183], v[174:175], v[180:181] op_sel_hi:[1,0]
	v_add_f32_e32 v132, v128, v129
	v_add_f32_e32 v134, v130, v131
	v_add_f32_e32 v110, v50, v202
	v_pk_mul_f32 v[184:185], v[172:173], v[180:181] op_sel:[0,1]
	v_pk_mul_f32 v[186:187], v[174:175], v[180:181] op_sel:[0,1]
	v_add_f32_dpp v132, v132, v132 quad_perm:[1,0,3,2] row_mask:0xf bank_mask:0xf bound_ctrl:1
	v_mul_f32_e32 v110, 0xbfb8aa3b, v110
	v_add_f32_dpp v134, v134, v134 quad_perm:[1,0,3,2] row_mask:0xf bank_mask:0xf bound_ctrl:1
	v_pk_fma_f32 v[136:137], v[116:117], v[160:161], v[136:137]
	v_add_f32_dpp v132, v132, v132 quad_perm:[2,3,0,1] row_mask:0xf bank_mask:0xf bound_ctrl:1
	v_exp_f32_e32 v110, v110
	v_add_f32_dpp v134, v134, v134 quad_perm:[2,3,0,1] row_mask:0xf bank_mask:0xf bound_ctrl:1
	v_pk_fma_f32 v[182:183], v[118:119], v[162:163], v[182:183]
	v_add_f32_dpp v132, v132, v132 row_half_mirror row_mask:0xf bank_mask:0xf bound_ctrl:1
	v_mfma_f32_16x16x32_bf16 v[206:209], v[14:17], v[74:77], v[206:209]
	v_add_f32_dpp v134, v134, v134 row_half_mirror row_mask:0xf bank_mask:0xf bound_ctrl:1
	v_pk_fma_f32 v[184:185], v[120:121], v[160:161], v[184:185]
	v_add_f32_dpp v132, v132, v132 row_mirror row_mask:0xf bank_mask:0xf bound_ctrl:1
	v_mov_b32_e32 v249, 0
	v_add_f32_dpp v134, v134, v134 row_mirror row_mask:0xf bank_mask:0xf bound_ctrl:1
	v_pk_fma_f32 v[186:187], v[122:123], v[162:163], v[186:187]
	v_pk_fma_f32 v[116:117], v[168:169], v[132:133], v[136:137] op_sel_hi:[1,0,1] neg_lo:[1,0,0] neg_hi:[1,0,0]
	v_add_u32_e32 v62, s28, v1
	v_pk_fma_f32 v[118:119], v[170:171], v[132:133], v[182:183] op_sel_hi:[1,0,1] neg_lo:[1,0,0] neg_hi:[1,0,0]
	v_pk_fma_f32 v[120:121], v[168:169], v[134:135], v[184:185] op_sel_hi:[1,0,1] neg_lo:[1,0,0] neg_hi:[1,0,0]
	v_pk_fma_f32 v[122:123], v[170:171], v[134:135], v[186:187] op_sel_hi:[1,0,1] neg_lo:[1,0,0] neg_hi:[1,0,0]
	v_readlane_b32 s0, v252, 48
	v_pk_mul_f32 v[188:189], v[116:117], v[176:177]
	v_pk_mul_f32 v[190:191], v[120:121], v[176:177]
	v_pk_fma_f32 v[188:189], v[118:119], v[178:179], v[188:189]
	v_and_b32_e32 v64, 0xfffffeff, v62
	v_pk_fma_f32 v[190:191], v[122:123], v[178:179], v[190:191]
	v_add_f32_e32 v246, v188, v189
	v_add_f32_e32 v247, v190, v191
	v_and_b32_e32 v66, 0xfffff7ff, v62
	ds_write_b64 v159, v[246:247] offset:56320
	ds_read_b128 v[164:167], v244 offset:6528
	ds_read_b128 v[160:163], v244 offset:2176
	v_add_u32_e32 v62, s0, v62
	ds_read_b128 v[172:175], v244 offset:15232
	ds_read_b128 v[168:171], v244 offset:10880
	s_movk_i32 s0, 0xb00
	ds_read_b128 v[176:179], v244 offset:19584
	ds_read_b64 v[180:181], v245 offset:23936
	s_waitcnt lgkmcnt(9)
; DI float red16(float x) { x = red8(x); x += dppf<0x140>(x); return x; }
; DI void scan_task(const Params& p, int l, int b, int h, int dir, int half, char* lds) {
;     ...
;   auto issue_loads = [&](int c) {
;     const int slo = chunk_lo(c);
;     const int s = slo + st_p;
;     const bool hasprev = (s != 0 && s != NCTX), hasnext = (s != NCTX - 1 && s != TB - 1);
;     const bf16_t* pa = p.PA + (size_t)(b * TB + s) * LDPA + hc + c4 * 4;
;     const int op = hasprev ? -LDPA : 0, on = hasnext ? LDPA : 0;
;     mprev = hasprev ? 1.f : 0.f; mnext = hasnext ? 1.f : 0.f;
; #pragma unroll
;     for (int sec = 0; sec < 3; ++sec) {
;       ld[sec][1] = *(const u32x2*)(pa + sec * 384);
;       ld[sec][0] = *(const u32x2*)(pa + sec * 384 + op);
;       ld[sec][2] = *(const u32x2*)(pa + sec * 384 + on);
;     }
;     const size_t trow = (size_t)(b * TB + slo + fr) * 64;
; #pragma unroll
;     for (int ks = 0; ks < 2; ++ks) { aw[ks] = *(const bf16x8*)(p.TW + trow + ks * 32 + fq * 8); aa[ks] = *(const bf16x8*)(p.TA + trow + ks * 32 + fq * 8); }
;     ...
;         const f32x2 kk0 = {ckk[0], ckk[1]}, kk1 = {ckk[2], ckk[3]}, w0 = {cw[0], cw[1]}, w1 = {cw[2], cw[3]};
;         const f32x2 b0 = {cbb[0], cbb[1]}, b1 = {cbb[2], cbb[3]}, kd0 = {ckd[0], ckd[1]}, kd1 = {ckd[2], ckd[3]};
;         const f32x2 r0 = {crr[0], crr[1]}, r1 = {crr[2], crr[3]};
;         const f32x2 p0 = S0[0] * kk0 + S0[1] * kk1, p1 = S1[0] * kk0 + S1[1] * kk1;
;         const f32x2 u00 = S0[0] * w0 + kd0 * cvv[0], u01 = S0[1] * w1 + kd1 * cvv[0];
;         const f32x2 u10 = S1[0] * w0 + kd0 * cvv[1], u11 = S1[1] * w1 + kd1 * cvv[1];
;         const float q0 = red16(p0[0] + p0[1]), q1 = red16(p1[0] + p1[1]);
;         S0[0] = u00 - b0 * q0; S0[1] = u01 - b1 * q0;
;         S1[0] = u10 - b0 * q1; S1[1] = u11 - b1 * q1;
;         const f32x2 y0 = S0[0] * r0 + S0[1] * r1, y1 = S1[0] * r0 + S1[1] * r1;
;         *(f32x2*)py = (f32x2){y0[0] + y0[1], y1[0] + y1[1]};
;         py += dir ? -512 : 512;
;         cw = nw; ckk = nkk; cbb = nbb; ckd = nkd; crr = nrr; cvv = nvv;
;       }
;     }
;     __syncthreads();
;     {
;       const int slo = chunk_lo(c);
;       const float* yp = ybuf + (st_p * 16 + c4) * 32;
;       f32x4 a = *(const f32x4*)(yp + 4 * (c4 & 7));
; #pragma unroll
;       for (int i = 1; i < 8; ++i) a += *(const f32x4*)(yp + 4 * ((i + c4) & 7));
	v_mad_i64_i32 v[62:63], s[0:1], v62, s0, v[102:103]
	v_pk_mul_f32 v[128:129], v[116:117], v[226:227]
	v_pk_mul_f32 v[130:131], v[120:121], v[226:227]
	v_pk_fma_f32 v[128:129], v[118:119], v[228:229], v[128:129]
	v_cmp_eq_u32_e32 vcc, 0, v64
	v_pk_fma_f32 v[130:131], v[122:123], v[228:229], v[130:131]
	v_pk_mul_f32 v[136:137], v[234:235], v[242:243] op_sel_hi:[1,0]
	v_pk_mul_f32 v[182:183], v[236:237], v[242:243] op_sel_hi:[1,0]
	v_cmp_eq_u32_e64 s[0:1], s33, v66
	v_add_f32_e32 v132, v128, v129
	v_add_f32_e32 v134, v130, v131
	v_pk_mul_f32 v[184:185], v[234:235], v[242:243] op_sel:[0,1]
	v_cndmask_b32_e64 v65, -1, 0, vcc
	v_pk_mul_f32 v[186:187], v[236:237], v[242:243] op_sel:[0,1]
	v_add_f32_dpp v132, v132, v132 quad_perm:[1,0,3,2] row_mask:0xf bank_mask:0xf bound_ctrl:1
	v_add_f32_dpp v134, v134, v134 quad_perm:[1,0,3,2] row_mask:0xf bank_mask:0xf bound_ctrl:1
	v_cndmask_b32_e64 v64, v150, 0, vcc
	v_pk_fma_f32 v[136:137], v[116:117], v[222:223], v[136:137]
	v_add_f32_dpp v132, v132, v132 quad_perm:[2,3,0,1] row_mask:0xf bank_mask:0xf bound_ctrl:1
	v_add_f32_dpp v134, v134, v134 quad_perm:[2,3,0,1] row_mask:0xf bank_mask:0xf bound_ctrl:1
	v_cndmask_b32_e64 v248, v151, 0, s[0:1]
	v_pk_fma_f32 v[182:183], v[118:119], v[224:225], v[182:183]
	v_add_f32_dpp v132, v132, v132 row_half_mirror row_mask:0xf bank_mask:0xf bound_ctrl:1
	v_add_f32_dpp v134, v134, v134 row_half_mirror row_mask:0xf bank_mask:0xf bound_ctrl:1
	v_lshl_add_u64 v[64:65], v[62:63], 0, v[64:65]
	v_pk_fma_f32 v[184:185], v[120:121], v[222:223], v[184:185]
	v_add_f32_dpp v132, v132, v132 row_mirror row_mask:0xf bank_mask:0xf bound_ctrl:1
	v_add_f32_dpp v134, v134, v134 row_mirror row_mask:0xf bank_mask:0xf bound_ctrl:1
	v_lshl_add_u64 v[66:67], v[62:63], 0, v[248:249]
	v_pk_fma_f32 v[186:187], v[122:123], v[224:225], v[186:187]
	v_pk_fma_f32 v[116:117], v[230:231], v[132:133], v[136:137] op_sel_hi:[1,0,1] neg_lo:[1,0,0] neg_hi:[1,0,0]
	v_pk_fma_f32 v[118:119], v[232:233], v[132:133], v[182:183] op_sel_hi:[1,0,1] neg_lo:[1,0,0] neg_hi:[1,0,0]
	global_load_dwordx2 v[78:79], v[62:63], off
	v_pk_fma_f32 v[120:121], v[230:231], v[134:135], v[184:185] op_sel_hi:[1,0,1] neg_lo:[1,0,0] neg_hi:[1,0,0]
	v_pk_fma_f32 v[122:123], v[232:233], v[134:135], v[186:187] op_sel_hi:[1,0,1] neg_lo:[1,0,0] neg_hi:[1,0,0]
	v_pk_mul_f32 v[188:189], v[116:117], v[238:239]
	global_load_dwordx2 v[80:81], v[64:65], off
	v_pk_mul_f32 v[190:191], v[120:121], v[238:239]
	v_pk_fma_f32 v[188:189], v[118:119], v[240:241], v[188:189]
	v_pk_fma_f32 v[190:191], v[122:123], v[240:241], v[190:191]
	global_load_dwordx2 v[82:83], v[62:63], off offset:768
	v_add_f32_e32 v246, v188, v189
	v_add_f32_e32 v247, v190, v191
	ds_write_b64 v159, v[246:247] offset:58368
	global_load_dwordx2 v[86:87], v[62:63], off offset:1536
	ds_read_b128 v[192:195], v124 offset:52224
	ds_read_b128 v[196:199], v124 offset:52240
	s_mul_i32 s20, s26, 7
	global_load_dwordx2 v[84:85], v[66:67], off
	s_add_i32 s20, s20, 4
	s_add_i32 s20, s20, s27
	s_waitcnt lgkmcnt(0)
	global_load_dwordx2 v[88:89], v[64:65], off offset:768
	v_pk_add_f32 v[192:193], v[192:193], v[194:195]
	v_pk_add_f32 v[196:197], v[196:197], v[198:199]
	s_add_i32 s20, s20, s100
	global_load_dwordx2 v[90:91], v[66:67], off offset:768
	v_pk_add_f32 v[192:193], v[192:193], v[196:197]
	s_mulk_i32 s20, 0x600
	s_nop 0
	global_load_dwordx2 v[92:93], v[64:65], off offset:1536
	v_add_f32_dpp v192, v192, v192 quad_perm:[1,0,3,2] row_mask:0xf bank_mask:0xf bound_ctrl:1
	v_add_f32_dpp v193, v193, v193 quad_perm:[1,0,3,2] row_mask:0xf bank_mask:0xf bound_ctrl:1
	v_add_u32_e32 v125, s20, v200
	global_load_dwordx2 v[94:95], v[66:67], off offset:1536
	v_add_f32_dpp v192, v192, v192 quad_perm:[2,3,0,1] row_mask:0xf bank_mask:0xf bound_ctrl:1
	v_add_f32_dpp v193, v193, v193 quad_perm:[2,3,0,1] row_mask:0xf bank_mask:0xf bound_ctrl:1
	global_store_dwordx2 v125, v[192:193], s[98:99]
	v_add_u32_e32 v62, s28, v127
	ds_read_b128 v[226:229], v244 offset:6800
	ds_read_b128 v[222:225], v244 offset:2448
	ds_read_b128 v[234:237], v244 offset:15504
	v_ashrrev_i32_e32 v63, 31, v62
	ds_read_b128 v[230:233], v244 offset:11152
	ds_read_b128 v[238:241], v244 offset:19856
	ds_read_b64 v[242:243], v245 offset:24208
	v_lshlrev_b64 v[62:63], 7, v[62:63]
	v_pk_mul_f32 v[128:129], v[116:117], v[164:165]
	v_pk_mul_f32 v[130:131], v[120:121], v[164:165]
	v_lshl_add_u64 v[66:67], v[106:107], 0, v[62:63]
	v_pk_fma_f32 v[128:129], v[118:119], v[166:167], v[128:129]
	v_pk_fma_f32 v[130:131], v[122:123], v[166:167], v[130:131]
	v_pk_mul_f32 v[136:137], v[172:173], v[180:181] op_sel_hi:[1,0]
	v_lshl_add_u64 v[74:75], v[108:109], 0, v[62:63]
	v_pk_mul_f32 v[182:183], v[174:175], v[180:181] op_sel_hi:[1,0]
	v_add_f32_e32 v132, v128, v129
	v_add_f32_e32 v134, v130, v131
	global_load_dwordx4 v[62:65], v[66:67], off
	v_pk_mul_f32 v[184:185], v[172:173], v[180:181] op_sel:[0,1]
	v_pk_mul_f32 v[186:187], v[174:175], v[180:181] op_sel:[0,1]
	v_add_f32_dpp v132, v132, v132 quad_perm:[1,0,3,2] row_mask:0xf bank_mask:0xf bound_ctrl:1
	global_load_dwordx4 v[66:69], v[66:67], off offset:64
	v_add_f32_dpp v134, v134, v134 quad_perm:[1,0,3,2] row_mask:0xf bank_mask:0xf bound_ctrl:1
	v_pk_fma_f32 v[136:137], v[116:117], v[160:161], v[136:137]
	v_add_f32_dpp v132, v132, v132 quad_perm:[2,3,0,1] row_mask:0xf bank_mask:0xf bound_ctrl:1
	global_load_dwordx4 v[70:73], v[74:75], off
	v_add_f32_dpp v134, v134, v134 quad_perm:[2,3,0,1] row_mask:0xf bank_mask:0xf bound_ctrl:1
	v_pk_fma_f32 v[182:183], v[118:119], v[162:163], v[182:183]
	global_load_dwordx4 v[74:77], v[74:75], off offset:64
	v_add_f32_dpp v132, v132, v132 row_half_mirror row_mask:0xf bank_mask:0xf bound_ctrl:1
; DI float sigmoidf_(float x) { return __builtin_amdgcn_rcpf(1.f + __expf(-x)); }
; DI float red16(float x) { x = red8(x); x += dppf<0x140>(x); return x; }
; DI void scan_task(const Params& p, int l, int b, int h, int dir, int half, char* lds) {
;     ...
;       const f32x4 kv = *(const f32x4*)(tk + fr * CS + colB);
;       const f32x4 kkv = *(const f32x4*)(cb + VKK * CP + fr * CS + colB);
;       f32x4 wv, kdv, bv;
; #pragma unroll
;       for (int j = 0; j < 4; ++j) {
;         wv[j] = __expf(-LOG_DECAY_SCALE * sigmoidf_(w0[j] + dw[j]));
;         const float a = sigmoidf_(a0[j] + da[j]);
;         kdv[j] = kv[j] * (1.f + (a - 1.f) * kag[j]);
;         bv[j] = kkv[j] * a;
;       }
;     ...
;         const f32x2 kk0 = {ckk[0], ckk[1]}, kk1 = {ckk[2], ckk[3]}, w0 = {cw[0], cw[1]}, w1 = {cw[2], cw[3]};
;         const f32x2 b0 = {cbb[0], cbb[1]}, b1 = {cbb[2], cbb[3]}, kd0 = {ckd[0], ckd[1]}, kd1 = {ckd[2], ckd[3]};
;         const f32x2 r0 = {crr[0], crr[1]}, r1 = {crr[2], crr[3]};
;         const f32x2 p0 = S0[0] * kk0 + S0[1] * kk1, p1 = S1[0] * kk0 + S1[1] * kk1;
;         const f32x2 u00 = S0[0] * w0 + kd0 * cvv[0], u01 = S0[1] * w1 + kd1 * cvv[0];
;         const f32x2 u10 = S1[0] * w0 + kd0 * cvv[1], u11 = S1[1] * w1 + kd1 * cvv[1];
;         const float q0 = red16(p0[0] + p0[1]), q1 = red16(p1[0] + p1[1]);
;         S0[0] = u00 - b0 * q0; S0[1] = u01 - b1 * q0;
;         S1[0] = u10 - b0 * q1; S1[1] = u11 - b1 * q1;
;         const f32x2 y0 = S0[0] * r0 + S0[1] * r1, y1 = S1[0] * r0 + S1[1] * r1;
;         *(f32x2*)py = (f32x2){y0[0] + y0[1], y1[0] + y1[1]};
;         py += dir ? -512 : 512;
	v_add_f32_dpp v134, v134, v134 row_half_mirror row_mask:0xf bank_mask:0xf bound_ctrl:1
	v_pk_fma_f32 v[184:185], v[120:121], v[160:161], v[184:185]
	v_cndmask_b32_e64 v96, 1.0, 0, vcc
	v_add_f32_dpp v132, v132, v132 row_mirror row_mask:0xf bank_mask:0xf bound_ctrl:1
	v_add_f32_dpp v134, v134, v134 row_mirror row_mask:0xf bank_mask:0xf bound_ctrl:1
	v_pk_fma_f32 v[186:187], v[122:123], v[162:163], v[186:187]
	v_cndmask_b32_e64 v98, 1.0, 0, s[0:1]
	v_pk_fma_f32 v[116:117], v[168:169], v[132:133], v[136:137] op_sel_hi:[1,0,1] neg_lo:[1,0,0] neg_hi:[1,0,0]
	v_pk_fma_f32 v[118:119], v[170:171], v[132:133], v[182:183] op_sel_hi:[1,0,1] neg_lo:[1,0,0] neg_hi:[1,0,0]
	v_pk_fma_f32 v[120:121], v[168:169], v[134:135], v[184:185] op_sel_hi:[1,0,1] neg_lo:[1,0,0] neg_hi:[1,0,0]
	v_add_f32_e32 v201, v51, v203
	v_pk_fma_f32 v[122:123], v[170:171], v[134:135], v[186:187] op_sel_hi:[1,0,1] neg_lo:[1,0,0] neg_hi:[1,0,0]
	v_pk_mul_f32 v[188:189], v[116:117], v[176:177]
	v_pk_mul_f32 v[190:191], v[120:121], v[176:177]
	v_mul_f32_e32 v201, 0xbfb8aa3b, v201
	v_pk_fma_f32 v[188:189], v[118:119], v[178:179], v[188:189]
	v_pk_fma_f32 v[190:191], v[122:123], v[178:179], v[190:191]
	v_add_f32_e32 v246, v188, v189
	v_exp_f32_e32 v201, v201
	v_add_f32_e32 v247, v190, v191
	ds_write_b64 v159, v[246:247] offset:52224
	ds_read_b128 v[164:167], v244 offset:7072
	v_add_f32_e32 v110, 1.0, v110
	ds_read_b128 v[160:163], v244 offset:2720
	ds_read_b128 v[172:175], v244 offset:15776
	ds_read_b128 v[168:171], v244 offset:11424
	v_rcp_f32_e32 v110, v110
	ds_read_b128 v[176:179], v244 offset:20128
	ds_read_b64 v[180:181], v245 offset:24480
	s_waitcnt lgkmcnt(7)
	v_add_f32_e32 v202, v54, v206
	v_pk_mul_f32 v[128:129], v[116:117], v[226:227]
	v_pk_mul_f32 v[130:131], v[120:121], v[226:227]
	v_pk_fma_f32 v[128:129], v[118:119], v[228:229], v[128:129]
	v_mul_f32_e32 v202, 0xbfb8aa3b, v202
	v_pk_fma_f32 v[130:131], v[122:123], v[228:229], v[130:131]
	v_pk_mul_f32 v[136:137], v[234:235], v[242:243] op_sel_hi:[1,0]
	v_pk_mul_f32 v[182:183], v[236:237], v[242:243] op_sel_hi:[1,0]
	v_exp_f32_e32 v203, v202
	v_add_f32_e32 v132, v128, v129
	v_add_f32_e32 v134, v130, v131
	v_pk_mul_f32 v[184:185], v[234:235], v[242:243] op_sel:[0,1]
	v_add_f32_e32 v201, 1.0, v201
	v_pk_mul_f32 v[186:187], v[236:237], v[242:243] op_sel:[0,1]
	v_add_f32_dpp v132, v132, v132 quad_perm:[1,0,3,2] row_mask:0xf bank_mask:0xf bound_ctrl:1
	v_add_f32_dpp v134, v134, v134 quad_perm:[1,0,3,2] row_mask:0xf bank_mask:0xf bound_ctrl:1
	v_rcp_f32_e32 v201, v201
	v_pk_fma_f32 v[136:137], v[116:117], v[222:223], v[136:137]
	v_add_f32_dpp v132, v132, v132 quad_perm:[2,3,0,1] row_mask:0xf bank_mask:0xf bound_ctrl:1
	v_add_f32_dpp v134, v134, v134 quad_perm:[2,3,0,1] row_mask:0xf bank_mask:0xf bound_ctrl:1
	v_mul_f32_e32 v110, 0xbf1b459e, v110
	v_pk_fma_f32 v[182:183], v[118:119], v[224:225], v[182:183]
	v_add_f32_dpp v132, v132, v132 row_half_mirror row_mask:0xf bank_mask:0xf bound_ctrl:1
	v_add_f32_dpp v134, v134, v134 row_half_mirror row_mask:0xf bank_mask:0xf bound_ctrl:1
	v_mul_f32_e32 v110, 0x3fb8aa3b, v110
	v_pk_fma_f32 v[184:185], v[120:121], v[222:223], v[184:185]
	v_add_f32_dpp v132, v132, v132 row_mirror row_mask:0xf bank_mask:0xf bound_ctrl:1
	v_add_f32_dpp v134, v134, v134 row_mirror row_mask:0xf bank_mask:0xf bound_ctrl:1
	v_exp_f32_e32 v202, v110
	v_pk_fma_f32 v[186:187], v[122:123], v[224:225], v[186:187]
	v_pk_fma_f32 v[116:117], v[230:231], v[132:133], v[136:137] op_sel_hi:[1,0,1] neg_lo:[1,0,0] neg_hi:[1,0,0]
	v_pk_fma_f32 v[118:119], v[232:233], v[132:133], v[182:183] op_sel_hi:[1,0,1] neg_lo:[1,0,0] neg_hi:[1,0,0]
	v_add_f32_e32 v110, 1.0, v203
	v_pk_fma_f32 v[120:121], v[230:231], v[134:135], v[184:185] op_sel_hi:[1,0,1] neg_lo:[1,0,0] neg_hi:[1,0,0]
	v_pk_fma_f32 v[122:123], v[232:233], v[134:135], v[186:187] op_sel_hi:[1,0,1] neg_lo:[1,0,0] neg_hi:[1,0,0]
	v_pk_mul_f32 v[188:189], v[116:117], v[238:239]
	v_rcp_f32_e32 v218, v110
	v_pk_mul_f32 v[190:191], v[120:121], v[238:239]
	v_pk_fma_f32 v[188:189], v[118:119], v[240:241], v[188:189]
	v_pk_fma_f32 v[190:191], v[122:123], v[240:241], v[190:191]
	v_mul_f32_e32 v110, 0xbf1b459e, v201
	v_add_f32_e32 v246, v188, v189
	v_add_f32_e32 v247, v190, v191
	ds_write_b64 v159, v[246:247] offset:54272
	v_add_f32_e32 v201, v52, v204
	ds_read_b128 v[226:229], v244 offset:7344
	ds_read_b128 v[222:225], v244 offset:2992
	ds_read_b128 v[234:237], v244 offset:16048
	v_mul_f32_e32 v201, 0xbfb8aa3b, v201
	ds_read_b128 v[230:233], v244 offset:11696
	ds_read_b128 v[238:241], v244 offset:20400
	ds_read_b64 v[242:243], v245 offset:24752
	v_exp_f32_e32 v201, v201
	s_waitcnt lgkmcnt(7)
; DI float sigmoidf_(float x) { return __builtin_amdgcn_rcpf(1.f + __expf(-x)); }
; DI float red16(float x) { x = red8(x); x += dppf<0x140>(x); return x; }
; DI void scan_task(const Params& p, int l, int b, int h, int dir, int half, char* lds) {
;     ...
;       const f32x4 kv = *(const f32x4*)(tk + fr * CS + colB);
;       const f32x4 kkv = *(const f32x4*)(cb + VKK * CP + fr * CS + colB);
;       f32x4 wv, kdv, bv;
; #pragma unroll
;       for (int j = 0; j < 4; ++j) {
;         wv[j] = __expf(-LOG_DECAY_SCALE * sigmoidf_(w0[j] + dw[j]));
;         const float a = sigmoidf_(a0[j] + da[j]);
;         kdv[j] = kv[j] * (1.f + (a - 1.f) * kag[j]);
;         bv[j] = kkv[j] * a;
;       }
;     ...
;         const f32x2 kk0 = {ckk[0], ckk[1]}, kk1 = {ckk[2], ckk[3]}, w0 = {cw[0], cw[1]}, w1 = {cw[2], cw[3]};
;         const f32x2 b0 = {cbb[0], cbb[1]}, b1 = {cbb[2], cbb[3]}, kd0 = {ckd[0], ckd[1]}, kd1 = {ckd[2], ckd[3]};
;         const f32x2 r0 = {crr[0], crr[1]}, r1 = {crr[2], crr[3]};
;         const f32x2 p0 = S0[0] * kk0 + S0[1] * kk1, p1 = S1[0] * kk0 + S1[1] * kk1;
;         const f32x2 u00 = S0[0] * w0 + kd0 * cvv[0], u01 = S0[1] * w1 + kd1 * cvv[0];
;         const f32x2 u10 = S1[0] * w0 + kd0 * cvv[1], u11 = S1[1] * w1 + kd1 * cvv[1];
;         const float q0 = red16(p0[0] + p0[1]), q1 = red16(p1[0] + p1[1]);
;         S0[0] = u00 - b0 * q0; S0[1] = u01 - b1 * q0;
;         S1[0] = u10 - b0 * q1; S1[1] = u11 - b1 * q1;
;         const f32x2 y0 = S0[0] * r0 + S0[1] * r1, y1 = S1[0] * r0 + S1[1] * r1;
;         *(f32x2*)py = (f32x2){y0[0] + y0[1], y1[0] + y1[1]};
;         py += dir ? -512 : 512;
;         cw = nw; ckk = nkk; cbb = nbb; ckd = nkd; crr = nrr; cvv = nvv;
;       }
;     }
;     __syncthreads();
;     {
;       const int slo = chunk_lo(c);
;       const float* yp = ybuf + (st_p * 16 + c4) * 32;
;       f32x4 a = *(const f32x4*)(yp + 4 * (c4 & 7));
; #pragma unroll
;       for (int i = 1; i < 8; ++i) a += *(const f32x4*)(yp + 4 * ((i + c4) & 7));
;       *(f32x2*)(p.Y + (size_t)dir * T_TOK * 384 + (size_t)(b * TB + slo + st_p) * 384 + hc + half * 32 + c4 * 2) = (f32x2){a[0] + a[2], a[1] + a[3]};
	v_pk_mul_f32 v[128:129], v[116:117], v[164:165]
	v_pk_mul_f32 v[130:131], v[120:121], v[164:165]
	v_add_f32_e32 v203, v55, v207
	v_pk_fma_f32 v[128:129], v[118:119], v[166:167], v[128:129]
	v_pk_fma_f32 v[130:131], v[122:123], v[166:167], v[130:131]
	v_pk_mul_f32 v[136:137], v[172:173], v[180:181] op_sel_hi:[1,0]
	v_mul_f32_e32 v203, 0xbfb8aa3b, v203
	v_pk_mul_f32 v[182:183], v[174:175], v[180:181] op_sel_hi:[1,0]
	v_add_f32_e32 v132, v128, v129
	v_add_f32_e32 v134, v130, v131
	v_exp_f32_e32 v204, v203
	v_pk_mul_f32 v[184:185], v[172:173], v[180:181] op_sel:[0,1]
	v_pk_mul_f32 v[186:187], v[174:175], v[180:181] op_sel:[0,1]
	v_add_f32_e32 v201, 1.0, v201
	v_add_f32_dpp v132, v132, v132 quad_perm:[1,0,3,2] row_mask:0xf bank_mask:0xf bound_ctrl:1
	v_add_f32_dpp v134, v134, v134 quad_perm:[1,0,3,2] row_mask:0xf bank_mask:0xf bound_ctrl:1
	v_pk_fma_f32 v[136:137], v[116:117], v[160:161], v[136:137]
	v_rcp_f32_e32 v201, v201
	v_add_f32_dpp v132, v132, v132 quad_perm:[2,3,0,1] row_mask:0xf bank_mask:0xf bound_ctrl:1
	v_add_f32_dpp v134, v134, v134 quad_perm:[2,3,0,1] row_mask:0xf bank_mask:0xf bound_ctrl:1
	v_pk_fma_f32 v[182:183], v[118:119], v[162:163], v[182:183]
	v_mul_f32_e32 v110, 0x3fb8aa3b, v110
	v_add_f32_dpp v132, v132, v132 row_half_mirror row_mask:0xf bank_mask:0xf bound_ctrl:1
	v_add_f32_dpp v134, v134, v134 row_half_mirror row_mask:0xf bank_mask:0xf bound_ctrl:1
	v_pk_fma_f32 v[184:185], v[120:121], v[160:161], v[184:185]
	v_exp_f32_e32 v203, v110
	v_add_f32_dpp v132, v132, v132 row_mirror row_mask:0xf bank_mask:0xf bound_ctrl:1
	v_add_f32_dpp v134, v134, v134 row_mirror row_mask:0xf bank_mask:0xf bound_ctrl:1
	v_pk_fma_f32 v[186:187], v[122:123], v[162:163], v[186:187]
	v_add_f32_e32 v110, 1.0, v204
	v_pk_fma_f32 v[116:117], v[168:169], v[132:133], v[136:137] op_sel_hi:[1,0,1] neg_lo:[1,0,0] neg_hi:[1,0,0]
	v_pk_fma_f32 v[118:119], v[170:171], v[132:133], v[182:183] op_sel_hi:[1,0,1] neg_lo:[1,0,0] neg_hi:[1,0,0]
	v_pk_fma_f32 v[120:121], v[168:169], v[134:135], v[184:185] op_sel_hi:[1,0,1] neg_lo:[1,0,0] neg_hi:[1,0,0]
	v_rcp_f32_e32 v219, v110
	v_pk_fma_f32 v[122:123], v[170:171], v[134:135], v[186:187] op_sel_hi:[1,0,1] neg_lo:[1,0,0] neg_hi:[1,0,0]
	v_pk_mul_f32 v[188:189], v[116:117], v[176:177]
	v_pk_mul_f32 v[190:191], v[120:121], v[176:177]
	v_mul_f32_e32 v110, 0xbf1b459e, v201
	v_pk_fma_f32 v[188:189], v[118:119], v[178:179], v[188:189]
	v_pk_fma_f32 v[190:191], v[122:123], v[178:179], v[190:191]
	v_add_f32_e32 v246, v188, v189
	v_mul_f32_e32 v110, 0x3fb8aa3b, v110
	v_add_f32_e32 v247, v190, v191
	ds_write_b64 v159, v[246:247] offset:56320
	ds_read_b128 v[164:167], v244 offset:7616
	v_exp_f32_e32 v204, v110
	ds_read_b128 v[160:163], v244 offset:3264
	ds_read_b128 v[172:175], v244 offset:16320
	ds_read_b128 v[168:171], v244 offset:11968
	v_add_f32_e32 v110, v53, v205
	ds_read_b128 v[176:179], v244 offset:20672
	ds_read_b64 v[180:181], v245 offset:25024
	s_waitcnt lgkmcnt(7)
	v_mul_f32_e32 v110, 0xbfb8aa3b, v110
	v_pk_mul_f32 v[128:129], v[116:117], v[226:227]
	v_pk_mul_f32 v[130:131], v[120:121], v[226:227]
	v_pk_fma_f32 v[128:129], v[118:119], v[228:229], v[128:129]
	v_exp_f32_e32 v110, v110
	v_pk_fma_f32 v[130:131], v[122:123], v[228:229], v[130:131]
	v_pk_mul_f32 v[136:137], v[234:235], v[242:243] op_sel_hi:[1,0]
	v_pk_mul_f32 v[182:183], v[236:237], v[242:243] op_sel_hi:[1,0]
	v_add_f32_e32 v201, v56, v208
	v_add_f32_e32 v132, v128, v129
	v_add_f32_e32 v134, v130, v131
	v_pk_mul_f32 v[184:185], v[234:235], v[242:243] op_sel:[0,1]
	v_mul_f32_e32 v201, 0xbfb8aa3b, v201
	v_pk_mul_f32 v[186:187], v[236:237], v[242:243] op_sel:[0,1]
	v_add_f32_dpp v132, v132, v132 quad_perm:[1,0,3,2] row_mask:0xf bank_mask:0xf bound_ctrl:1
	v_add_f32_dpp v134, v134, v134 quad_perm:[1,0,3,2] row_mask:0xf bank_mask:0xf bound_ctrl:1
	v_add_f32_e32 v205, v57, v209
	v_pk_fma_f32 v[136:137], v[116:117], v[222:223], v[136:137]
	v_add_f32_dpp v132, v132, v132 quad_perm:[2,3,0,1] row_mask:0xf bank_mask:0xf bound_ctrl:1
	v_add_f32_dpp v134, v134, v134 quad_perm:[2,3,0,1] row_mask:0xf bank_mask:0xf bound_ctrl:1
	v_exp_f32_e32 v201, v201
	v_pk_fma_f32 v[182:183], v[118:119], v[224:225], v[182:183]
	v_add_f32_dpp v132, v132, v132 row_half_mirror row_mask:0xf bank_mask:0xf bound_ctrl:1
	v_add_f32_dpp v134, v134, v134 row_half_mirror row_mask:0xf bank_mask:0xf bound_ctrl:1
	v_mul_f32_e32 v205, 0xbfb8aa3b, v205
	v_pk_fma_f32 v[184:185], v[120:121], v[222:223], v[184:185]
	v_add_f32_dpp v132, v132, v132 row_mirror row_mask:0xf bank_mask:0xf bound_ctrl:1
	v_add_f32_dpp v134, v134, v134 row_mirror row_mask:0xf bank_mask:0xf bound_ctrl:1
	v_exp_f32_e32 v205, v205
	v_pk_fma_f32 v[186:187], v[122:123], v[224:225], v[186:187]
	v_pk_fma_f32 v[116:117], v[230:231], v[132:133], v[136:137] op_sel_hi:[1,0,1] neg_lo:[1,0,0] neg_hi:[1,0,0]
	v_pk_fma_f32 v[118:119], v[232:233], v[132:133], v[182:183] op_sel_hi:[1,0,1] neg_lo:[1,0,0] neg_hi:[1,0,0]
	v_add_f32_e32 v110, 1.0, v110
	v_pk_fma_f32 v[120:121], v[230:231], v[134:135], v[184:185] op_sel_hi:[1,0,1] neg_lo:[1,0,0] neg_hi:[1,0,0]
	v_pk_fma_f32 v[122:123], v[232:233], v[134:135], v[186:187] op_sel_hi:[1,0,1] neg_lo:[1,0,0] neg_hi:[1,0,0]
	v_pk_mul_f32 v[188:189], v[116:117], v[238:239]
	v_rcp_f32_e32 v110, v110
	v_pk_mul_f32 v[190:191], v[120:121], v[238:239]
	v_pk_fma_f32 v[188:189], v[118:119], v[240:241], v[188:189]
	v_pk_fma_f32 v[190:191], v[122:123], v[240:241], v[190:191]
	v_add_f32_e32 v201, 1.0, v201
	v_add_f32_e32 v246, v188, v189
	v_add_f32_e32 v247, v190, v191
	ds_write_b64 v159, v[246:247] offset:58368
	v_rcp_f32_e32 v220, v201
	ds_read_b128 v[192:195], v124 offset:52224
	ds_read_b128 v[196:199], v124 offset:52240
	s_mul_i32 s20, s26, -1
	v_add_f32_e32 v201, 1.0, v205
	s_add_i32 s20, s20, 8
	s_add_i32 s20, s20, s27
	s_waitcnt lgkmcnt(0)
; DI float sigmoidf_(float x) { return __builtin_amdgcn_rcpf(1.f + __expf(-x)); }
; DI float red16(float x) { x = red8(x); x += dppf<0x140>(x); return x; }
; DI void scan_task(const Params& p, int l, int b, int h, int dir, int half, char* lds) {
;     ...
; #pragma unroll
;       for (int j = 0; j < 4; ++j) {
;         wv[j] = __expf(-LOG_DECAY_SCALE * sigmoidf_(w0[j] + dw[j]));
;         const float a = sigmoidf_(a0[j] + da[j]);
;         kdv[j] = kv[j] * (1.f + (a - 1.f) * kag[j]);
;         bv[j] = kkv[j] * a;
;       }
;       *(f32x4*)(cb + VW * CP + fr * CS + colB) = wv;
;       *(f32x4*)(cb + VKD * CP + fr * CS + colB) = kdv;
;       *(f32x4*)(cb + VB * CP + fr * CS + colB) = bv;
;     }
;     __syncthreads();
;     {
;       const f32x4 rv = *(const f32x4*)(cb + VR * CP + st_p * CS + c4 * 4);
;       const f32x4 kdv = *(const f32x4*)(cb + VKD * CP + st_p * CS + c4 * 4);
;     ...
;         const f32x2 kk0 = {ckk[0], ckk[1]}, kk1 = {ckk[2], ckk[3]}, w0 = {cw[0], cw[1]}, w1 = {cw[2], cw[3]};
;         const f32x2 b0 = {cbb[0], cbb[1]}, b1 = {cbb[2], cbb[3]}, kd0 = {ckd[0], ckd[1]}, kd1 = {ckd[2], ckd[3]};
;         const f32x2 r0 = {crr[0], crr[1]}, r1 = {crr[2], crr[3]};
;         const f32x2 p0 = S0[0] * kk0 + S0[1] * kk1, p1 = S1[0] * kk0 + S1[1] * kk1;
;         const f32x2 u00 = S0[0] * w0 + kd0 * cvv[0], u01 = S0[1] * w1 + kd1 * cvv[0];
;         const f32x2 u10 = S1[0] * w0 + kd0 * cvv[1], u11 = S1[1] * w1 + kd1 * cvv[1];
;         const float q0 = red16(p0[0] + p0[1]), q1 = red16(p1[0] + p1[1]);
;         S0[0] = u00 - b0 * q0; S0[1] = u01 - b1 * q0;
;         S1[0] = u10 - b0 * q1; S1[1] = u11 - b1 * q1;
;         const f32x2 y0 = S0[0] * r0 + S0[1] * r1, y1 = S1[0] * r0 + S1[1] * r1;
;         *(f32x2*)py = (f32x2){y0[0] + y0[1], y1[0] + y1[1]};
;         py += dir ? -512 : 512;
;         cw = nw; ckk = nkk; cbb = nbb; ckd = nkd; crr = nrr; cvv = nvv;
;       }
;     }
;     __syncthreads();
;     {
;       const int slo = chunk_lo(c);
;       const float* yp = ybuf + (st_p * 16 + c4) * 32;
;       f32x4 a = *(const f32x4*)(yp + 4 * (c4 & 7));
; #pragma unroll
;       for (int i = 1; i < 8; ++i) a += *(const f32x4*)(yp + 4 * ((i + c4) & 7));
;       *(f32x2*)(p.Y + (size_t)dir * T_TOK * 384 + (size_t)(b * TB + slo + st_p) * 384 + hc + half * 32 + c4 * 2) = (f32x2){a[0] + a[2], a[1] + a[3]};
	v_rcp_f32_e32 v221, v201
	v_pk_add_f32 v[192:193], v[192:193], v[194:195]
	v_pk_add_f32 v[196:197], v[196:197], v[198:199]
	s_add_i32 s20, s20, s100
	v_mul_f32_e32 v110, 0xbf1b459e, v110
	v_pk_add_f32 v[192:193], v[192:193], v[196:197]
	s_mulk_i32 s20, 0x600
	v_mul_f32_e32 v110, 0x3fb8aa3b, v110
	s_nop 0
	v_add_f32_dpp v192, v192, v192 quad_perm:[1,0,3,2] row_mask:0xf bank_mask:0xf bound_ctrl:1
	v_add_f32_dpp v193, v193, v193 quad_perm:[1,0,3,2] row_mask:0xf bank_mask:0xf bound_ctrl:1
	v_exp_f32_e32 v205, v110
	v_add_u32_e32 v125, s20, v200
	v_add_f32_dpp v192, v192, v192 quad_perm:[2,3,0,1] row_mask:0xf bank_mask:0xf bound_ctrl:1
	v_add_f32_dpp v193, v193, v193 quad_perm:[2,3,0,1] row_mask:0xf bank_mask:0xf bound_ctrl:1
	v_pk_add_f32 v[206:207], v[218:219], -1.0 op_sel_hi:[1,0]
	global_store_dwordx2 v125, v[192:193], s[98:99]
	ds_read_b128 v[226:229], v244 offset:7888
	ds_read_b128 v[222:225], v244 offset:3536
	v_pk_add_f32 v[208:209], v[220:221], -1.0 op_sel_hi:[1,0]
	ds_read_b128 v[234:237], v244 offset:16592
	ds_read_b128 v[230:233], v244 offset:12240
	ds_read_b128 v[238:241], v244 offset:20944
	v_pk_fma_f32 v[206:207], v[58:59], v[206:207], 1.0 op_sel_hi:[1,1,0]
	ds_read_b64 v[242:243], v245 offset:25296
	v_pk_mul_f32 v[128:129], v[116:117], v[164:165]
	v_pk_fma_f32 v[208:209], v[60:61], v[208:209], 1.0 op_sel_hi:[1,1,0]
	v_pk_mul_f32 v[130:131], v[120:121], v[164:165]
	v_pk_fma_f32 v[128:129], v[118:119], v[166:167], v[128:129]
	v_pk_fma_f32 v[130:131], v[122:123], v[166:167], v[130:131]
	v_pk_mul_f32 v[136:137], v[172:173], v[180:181] op_sel_hi:[1,0]
	v_pk_mul_f32 v[182:183], v[174:175], v[180:181] op_sel_hi:[1,0]
	v_add_f32_e32 v132, v128, v129
	v_pk_mul_f32 v[206:207], v[210:211], v[206:207]
	v_add_f32_e32 v134, v130, v131
	v_pk_mul_f32 v[184:185], v[172:173], v[180:181] op_sel:[0,1]
	v_pk_mul_f32 v[186:187], v[174:175], v[180:181] op_sel:[0,1]
	v_pk_mul_f32 v[208:209], v[212:213], v[208:209]
	v_add_f32_dpp v132, v132, v132 quad_perm:[1,0,3,2] row_mask:0xf bank_mask:0xf bound_ctrl:1
	v_add_f32_dpp v134, v134, v134 quad_perm:[1,0,3,2] row_mask:0xf bank_mask:0xf bound_ctrl:1
	v_pk_fma_f32 v[136:137], v[116:117], v[160:161], v[136:137]
	v_add_f32_dpp v132, v132, v132 quad_perm:[2,3,0,1] row_mask:0xf bank_mask:0xf bound_ctrl:1
	v_add_f32_dpp v134, v134, v134 quad_perm:[2,3,0,1] row_mask:0xf bank_mask:0xf bound_ctrl:1
	v_pk_fma_f32 v[182:183], v[118:119], v[162:163], v[182:183]
	v_pk_mul_f32 v[210:211], v[214:215], v[218:219]
	v_add_f32_dpp v132, v132, v132 row_half_mirror row_mask:0xf bank_mask:0xf bound_ctrl:1
	v_add_f32_dpp v134, v134, v134 row_half_mirror row_mask:0xf bank_mask:0xf bound_ctrl:1
	v_pk_fma_f32 v[184:185], v[120:121], v[160:161], v[184:185]
	v_pk_mul_f32 v[212:213], v[216:217], v[220:221]
	v_add_f32_dpp v132, v132, v132 row_mirror row_mask:0xf bank_mask:0xf bound_ctrl:1
	v_add_f32_dpp v134, v134, v134 row_mirror row_mask:0xf bank_mask:0xf bound_ctrl:1
	v_pk_fma_f32 v[186:187], v[122:123], v[162:163], v[186:187]
	ds_write_b128 v97, v[202:205]
	v_pk_fma_f32 v[116:117], v[168:169], v[132:133], v[136:137] op_sel_hi:[1,0,1] neg_lo:[1,0,0] neg_hi:[1,0,0]
	v_pk_fma_f32 v[118:119], v[170:171], v[132:133], v[182:183] op_sel_hi:[1,0,1] neg_lo:[1,0,0] neg_hi:[1,0,0]
	v_pk_fma_f32 v[120:121], v[168:169], v[134:135], v[184:185] op_sel_hi:[1,0,1] neg_lo:[1,0,0] neg_hi:[1,0,0]
	ds_write_b128 v97, v[206:209] offset:13056
	v_pk_fma_f32 v[122:123], v[170:171], v[134:135], v[186:187] op_sel_hi:[1,0,1] neg_lo:[1,0,0] neg_hi:[1,0,0]
	v_pk_mul_f32 v[188:189], v[116:117], v[176:177]
	v_pk_mul_f32 v[190:191], v[120:121], v[176:177]
	ds_write_b128 v97, v[210:213] offset:8704
	v_pk_fma_f32 v[188:189], v[118:119], v[178:179], v[188:189]
	v_pk_fma_f32 v[190:191], v[122:123], v[178:179], v[190:191]
	v_add_f32_e32 v246, v188, v189
	s_waitcnt lgkmcnt(0)
	s_barrier
	v_add_f32_e32 v247, v190, v191
	ds_write_b64 v159, v[246:247] offset:52224
	ds_read_b128 v[164:167], v244 offset:8160
	ds_read_b128 v[202:205], v100 offset:17408
	ds_read_b128 v[160:163], v244 offset:3808
	ds_read_b128 v[172:175], v244 offset:16864
	ds_read_b128 v[168:171], v244 offset:12512
	ds_read_b128 v[206:209], v100 offset:13056
	ds_read_b128 v[176:179], v244 offset:21216
	ds_read_b64 v[180:181], v245 offset:25568
	s_waitcnt lgkmcnt(2)
; DI float red16(float x) { x = red8(x); x += dppf<0x140>(x); return x; }
; DI void scan_task(const Params& p, int l, int b, int h, int dir, int half, char* lds) {
;     ...
;       const f32x4 rv = *(const f32x4*)(cb + VR * CP + st_p * CS + c4 * 4);
;       const f32x4 kdv = *(const f32x4*)(cb + VKD * CP + st_p * CS + c4 * 4);
;       float bs = rv[0] * kdv[0] * rkg[0] + rv[1] * kdv[1] * rkg[1] + rv[2] * kdv[2] * rkg[2] + rv[3] * kdv[3] * rkg[3];
;       bs = red16(bs);
;       if (c4 == 0 && half == 0) p.BON[(size_t)dir * T_TOK * 6 + (size_t)(b * TB + slo + st_p) * 6 + h] = bs;
;     ...
;         const f32x2 kk0 = {ckk[0], ckk[1]}, kk1 = {ckk[2], ckk[3]}, w0 = {cw[0], cw[1]}, w1 = {cw[2], cw[3]};
;         const f32x2 b0 = {cbb[0], cbb[1]}, b1 = {cbb[2], cbb[3]}, kd0 = {ckd[0], ckd[1]}, kd1 = {ckd[2], ckd[3]};
;         const f32x2 r0 = {crr[0], crr[1]}, r1 = {crr[2], crr[3]};
;         const f32x2 p0 = S0[0] * kk0 + S0[1] * kk1, p1 = S1[0] * kk0 + S1[1] * kk1;
;         const f32x2 u00 = S0[0] * w0 + kd0 * cvv[0], u01 = S0[1] * w1 + kd1 * cvv[0];
;         const f32x2 u10 = S1[0] * w0 + kd0 * cvv[1], u11 = S1[1] * w1 + kd1 * cvv[1];
;         const float q0 = red16(p0[0] + p0[1]), q1 = red16(p1[0] + p1[1]);
;         S0[0] = u00 - b0 * q0; S0[1] = u01 - b1 * q0;
;         S1[0] = u10 - b0 * q1; S1[1] = u11 - b1 * q1;
;         const f32x2 y0 = S0[0] * r0 + S0[1] * r1, y1 = S1[0] * r0 + S1[1] * r1;
;         *(f32x2*)py = (f32x2){y0[0] + y0[1], y1[0] + y1[1]};
;         py += dir ? -512 : 512;
	v_pk_mul_f32 v[128:129], v[116:117], v[226:227]
	v_pk_mul_f32 v[130:131], v[120:121], v[226:227]
	v_pk_fma_f32 v[128:129], v[118:119], v[228:229], v[128:129]
	v_mul_f32_e32 v201, v203, v207
	v_pk_fma_f32 v[130:131], v[122:123], v[228:229], v[130:131]
	v_pk_mul_f32 v[136:137], v[234:235], v[242:243] op_sel_hi:[1,0]
	v_pk_mul_f32 v[182:183], v[236:237], v[242:243] op_sel_hi:[1,0]
	v_mul_f32_e32 v110, v202, v206
	v_add_f32_e32 v132, v128, v129
	v_add_f32_e32 v134, v130, v131
	v_pk_mul_f32 v[184:185], v[234:235], v[242:243] op_sel:[0,1]
	v_mul_f32_e32 v201, v47, v201
	v_pk_mul_f32 v[186:187], v[236:237], v[242:243] op_sel:[0,1]
	v_add_f32_dpp v132, v132, v132 quad_perm:[1,0,3,2] row_mask:0xf bank_mask:0xf bound_ctrl:1
	v_add_f32_dpp v134, v134, v134 quad_perm:[1,0,3,2] row_mask:0xf bank_mask:0xf bound_ctrl:1
	v_fmac_f32_e32 v201, v46, v110
	v_pk_fma_f32 v[136:137], v[116:117], v[222:223], v[136:137]
	v_add_f32_dpp v132, v132, v132 quad_perm:[2,3,0,1] row_mask:0xf bank_mask:0xf bound_ctrl:1
	v_add_f32_dpp v134, v134, v134 quad_perm:[2,3,0,1] row_mask:0xf bank_mask:0xf bound_ctrl:1
	v_mul_f32_e32 v110, v204, v208
	v_pk_fma_f32 v[182:183], v[118:119], v[224:225], v[182:183]
	v_add_f32_dpp v132, v132, v132 row_half_mirror row_mask:0xf bank_mask:0xf bound_ctrl:1
	v_add_f32_dpp v134, v134, v134 row_half_mirror row_mask:0xf bank_mask:0xf bound_ctrl:1
	v_fmac_f32_e32 v201, v48, v110
	v_pk_fma_f32 v[184:185], v[120:121], v[222:223], v[184:185]
	v_add_f32_dpp v132, v132, v132 row_mirror row_mask:0xf bank_mask:0xf bound_ctrl:1
	v_add_f32_dpp v134, v134, v134 row_mirror row_mask:0xf bank_mask:0xf bound_ctrl:1
	v_mul_f32_e32 v110, v205, v209
	v_pk_fma_f32 v[186:187], v[122:123], v[224:225], v[186:187]
	v_pk_fma_f32 v[116:117], v[230:231], v[132:133], v[136:137] op_sel_hi:[1,0,1] neg_lo:[1,0,0] neg_hi:[1,0,0]
	v_fmac_f32_e32 v201, v49, v110
	v_pk_fma_f32 v[118:119], v[232:233], v[132:133], v[182:183] op_sel_hi:[1,0,1] neg_lo:[1,0,0] neg_hi:[1,0,0]
	v_pk_fma_f32 v[120:121], v[230:231], v[134:135], v[184:185] op_sel_hi:[1,0,1] neg_lo:[1,0,0] neg_hi:[1,0,0]
	v_pk_fma_f32 v[122:123], v[232:233], v[134:135], v[186:187] op_sel_hi:[1,0,1] neg_lo:[1,0,0] neg_hi:[1,0,0]
	v_add_f32_dpp v110, v201, v201 quad_perm:[1,0,3,2] row_mask:0xf bank_mask:0xf bound_ctrl:1
	v_pk_mul_f32 v[188:189], v[116:117], v[238:239]
	v_pk_mul_f32 v[190:191], v[120:121], v[238:239]
	v_pk_fma_f32 v[188:189], v[118:119], v[240:241], v[188:189]
	v_add_f32_dpp v110, v110, v110 quad_perm:[2,3,0,1] row_mask:0xf bank_mask:0xf bound_ctrl:1
	v_pk_fma_f32 v[190:191], v[122:123], v[240:241], v[190:191]
	v_add_f32_e32 v246, v188, v189
	v_add_f32_e32 v247, v190, v191
	v_add_f32_dpp v110, v110, v110 row_half_mirror row_mask:0xf bank_mask:0xf bound_ctrl:1
	ds_write_b64 v159, v[246:247] offset:54272
	ds_read_b128 v[226:229], v244 offset:8432
	ds_read_b128 v[222:225], v244 offset:4080
	v_mov_b32_dpp v201, v110 row_mirror row_mask:0xf bank_mask:0xf bound_ctrl:1
	ds_read_b128 v[234:237], v244 offset:17136
	ds_read_b128 v[230:233], v244 offset:12784
	ds_read_b128 v[238:241], v244 offset:21488
	s_mov_b32 s2, s29
	s_and_saveexec_b64 s[0:1], s[36:37]
	v_add_f32_e32 v110, v110, v201
	v_add_u32_e32 v201, s2, v126
	v_readlane_b32 s2, v252, 50
	v_readlane_b32 s3, v252, 51
	s_nop 1
	v_mad_i64_i32 v[202:203], s[2:3], v201, 24, s[2:3]
	global_store_dword v[202:203], v110, off
	s_or_b64 exec, exec, s[0:1]
	s_nop 1
	ds_read_b64 v[242:243], v245 offset:25840
	s_waitcnt lgkmcnt(7)
; DI float red16(float x) { x = red8(x); x += dppf<0x140>(x); return x; }
; DI void scan_task(const Params& p, int l, int b, int h, int dir, int half, char* lds) {
;     ...
;         const f32x2 kk0 = {ckk[0], ckk[1]}, kk1 = {ckk[2], ckk[3]}, w0 = {cw[0], cw[1]}, w1 = {cw[2], cw[3]};
;         const f32x2 b0 = {cbb[0], cbb[1]}, b1 = {cbb[2], cbb[3]}, kd0 = {ckd[0], ckd[1]}, kd1 = {ckd[2], ckd[3]};
;         const f32x2 r0 = {crr[0], crr[1]}, r1 = {crr[2], crr[3]};
;         const f32x2 p0 = S0[0] * kk0 + S0[1] * kk1, p1 = S1[0] * kk0 + S1[1] * kk1;
;         const f32x2 u00 = S0[0] * w0 + kd0 * cvv[0], u01 = S0[1] * w1 + kd1 * cvv[0];
;         const f32x2 u10 = S1[0] * w0 + kd0 * cvv[1], u11 = S1[1] * w1 + kd1 * cvv[1];
;         const float q0 = red16(p0[0] + p0[1]), q1 = red16(p1[0] + p1[1]);
;         S0[0] = u00 - b0 * q0; S0[1] = u01 - b1 * q0;
;         S1[0] = u10 - b0 * q1; S1[1] = u11 - b1 * q1;
;         const f32x2 y0 = S0[0] * r0 + S0[1] * r1, y1 = S1[0] * r0 + S1[1] * r1;
;         *(f32x2*)py = (f32x2){y0[0] + y0[1], y1[0] + y1[1]};
;         py += dir ? -512 : 512;
;         cw = nw; ckk = nkk; cbb = nbb; ckd = nkd; crr = nrr; cvv = nvv;
;       }
;     }
;     __syncthreads();
;     {
;       const int slo = chunk_lo(c);
;       const float* yp = ybuf + (st_p * 16 + c4) * 32;
;       f32x4 a = *(const f32x4*)(yp + 4 * (c4 & 7));
; #pragma unroll
;       for (int i = 1; i < 8; ++i) a += *(const f32x4*)(yp + 4 * ((i + c4) & 7));
;       *(f32x2*)(p.Y + (size_t)dir * T_TOK * 384 + (size_t)(b * TB + slo + st_p) * 384 + hc + half * 32 + c4 * 2) = (f32x2){a[0] + a[2], a[1] + a[3]};
;     }
;     if (c + 1 < NCH) produce(c + 1);
;   }
	v_pk_mul_f32 v[128:129], v[116:117], v[164:165]
	v_pk_mul_f32 v[130:131], v[120:121], v[164:165]
	v_pk_fma_f32 v[128:129], v[118:119], v[166:167], v[128:129]
	v_pk_fma_f32 v[130:131], v[122:123], v[166:167], v[130:131]
	v_pk_mul_f32 v[136:137], v[172:173], v[180:181] op_sel_hi:[1,0]
	v_pk_mul_f32 v[182:183], v[174:175], v[180:181] op_sel_hi:[1,0]
	v_add_f32_e32 v132, v128, v129
	v_add_f32_e32 v134, v130, v131
	v_pk_mul_f32 v[184:185], v[172:173], v[180:181] op_sel:[0,1]
	v_pk_mul_f32 v[186:187], v[174:175], v[180:181] op_sel:[0,1]
	v_add_f32_dpp v132, v132, v132 quad_perm:[1,0,3,2] row_mask:0xf bank_mask:0xf bound_ctrl:1
	v_add_f32_dpp v134, v134, v134 quad_perm:[1,0,3,2] row_mask:0xf bank_mask:0xf bound_ctrl:1
	v_pk_fma_f32 v[136:137], v[116:117], v[160:161], v[136:137]
	v_add_f32_dpp v132, v132, v132 quad_perm:[2,3,0,1] row_mask:0xf bank_mask:0xf bound_ctrl:1
	v_add_f32_dpp v134, v134, v134 quad_perm:[2,3,0,1] row_mask:0xf bank_mask:0xf bound_ctrl:1
	v_pk_fma_f32 v[182:183], v[118:119], v[162:163], v[182:183]
	v_add_f32_dpp v132, v132, v132 row_half_mirror row_mask:0xf bank_mask:0xf bound_ctrl:1
	v_add_f32_dpp v134, v134, v134 row_half_mirror row_mask:0xf bank_mask:0xf bound_ctrl:1
	v_pk_fma_f32 v[184:185], v[120:121], v[160:161], v[184:185]
	v_add_f32_dpp v132, v132, v132 row_mirror row_mask:0xf bank_mask:0xf bound_ctrl:1
	v_add_f32_dpp v134, v134, v134 row_mirror row_mask:0xf bank_mask:0xf bound_ctrl:1
	v_pk_fma_f32 v[186:187], v[122:123], v[162:163], v[186:187]
	v_pk_fma_f32 v[116:117], v[168:169], v[132:133], v[136:137] op_sel_hi:[1,0,1] neg_lo:[1,0,0] neg_hi:[1,0,0]
	v_pk_fma_f32 v[118:119], v[170:171], v[132:133], v[182:183] op_sel_hi:[1,0,1] neg_lo:[1,0,0] neg_hi:[1,0,0]
	v_pk_fma_f32 v[120:121], v[168:169], v[134:135], v[184:185] op_sel_hi:[1,0,1] neg_lo:[1,0,0] neg_hi:[1,0,0]
	v_pk_fma_f32 v[122:123], v[170:171], v[134:135], v[186:187] op_sel_hi:[1,0,1] neg_lo:[1,0,0] neg_hi:[1,0,0]
	v_pk_mul_f32 v[188:189], v[116:117], v[176:177]
	v_pk_mul_f32 v[190:191], v[120:121], v[176:177]
	v_pk_fma_f32 v[188:189], v[118:119], v[178:179], v[188:189]
	v_pk_fma_f32 v[190:191], v[122:123], v[178:179], v[190:191]
	v_add_f32_e32 v246, v188, v189
	v_add_f32_e32 v247, v190, v191
	ds_write_b64 v159, v[246:247] offset:56320
	v_add_u32_e32 v244, s101, v244
	v_add_u32_e32 v245, s101, v245
	ds_read_b128 v[164:167], v244 offset:4352
	ds_read_b128 v[160:163], v244 offset:0
	ds_read_b128 v[172:175], v244 offset:13056
	ds_read_b128 v[168:171], v244 offset:8704
	ds_read_b128 v[176:179], v244 offset:17408
	ds_read_b64 v[180:181], v245 offset:21760
	s_waitcnt lgkmcnt(7)
	v_pk_mul_f32 v[128:129], v[116:117], v[226:227]
	v_pk_mul_f32 v[130:131], v[120:121], v[226:227]
	v_pk_fma_f32 v[128:129], v[118:119], v[228:229], v[128:129]
	v_pk_fma_f32 v[130:131], v[122:123], v[228:229], v[130:131]
	v_pk_mul_f32 v[136:137], v[234:235], v[242:243] op_sel_hi:[1,0]
	v_pk_mul_f32 v[182:183], v[236:237], v[242:243] op_sel_hi:[1,0]
	v_add_f32_e32 v132, v128, v129
	v_add_f32_e32 v134, v130, v131
	v_pk_mul_f32 v[184:185], v[234:235], v[242:243] op_sel:[0,1]
	v_pk_mul_f32 v[186:187], v[236:237], v[242:243] op_sel:[0,1]
	v_add_f32_dpp v132, v132, v132 quad_perm:[1,0,3,2] row_mask:0xf bank_mask:0xf bound_ctrl:1
	v_add_f32_dpp v134, v134, v134 quad_perm:[1,0,3,2] row_mask:0xf bank_mask:0xf bound_ctrl:1
	v_pk_fma_f32 v[136:137], v[116:117], v[222:223], v[136:137]
	v_add_f32_dpp v132, v132, v132 quad_perm:[2,3,0,1] row_mask:0xf bank_mask:0xf bound_ctrl:1
	v_add_f32_dpp v134, v134, v134 quad_perm:[2,3,0,1] row_mask:0xf bank_mask:0xf bound_ctrl:1
	v_pk_fma_f32 v[182:183], v[118:119], v[224:225], v[182:183]
	v_add_f32_dpp v132, v132, v132 row_half_mirror row_mask:0xf bank_mask:0xf bound_ctrl:1
	v_add_f32_dpp v134, v134, v134 row_half_mirror row_mask:0xf bank_mask:0xf bound_ctrl:1
	v_pk_fma_f32 v[184:185], v[120:121], v[222:223], v[184:185]
	v_add_f32_dpp v132, v132, v132 row_mirror row_mask:0xf bank_mask:0xf bound_ctrl:1
	v_add_f32_dpp v134, v134, v134 row_mirror row_mask:0xf bank_mask:0xf bound_ctrl:1
	v_pk_fma_f32 v[186:187], v[122:123], v[224:225], v[186:187]
	v_pk_fma_f32 v[116:117], v[230:231], v[132:133], v[136:137] op_sel_hi:[1,0,1] neg_lo:[1,0,0] neg_hi:[1,0,0]
	v_pk_fma_f32 v[118:119], v[232:233], v[132:133], v[182:183] op_sel_hi:[1,0,1] neg_lo:[1,0,0] neg_hi:[1,0,0]
	v_pk_fma_f32 v[120:121], v[230:231], v[134:135], v[184:185] op_sel_hi:[1,0,1] neg_lo:[1,0,0] neg_hi:[1,0,0]
	v_pk_fma_f32 v[122:123], v[232:233], v[134:135], v[186:187] op_sel_hi:[1,0,1] neg_lo:[1,0,0] neg_hi:[1,0,0]
	v_pk_mul_f32 v[188:189], v[116:117], v[238:239]
	v_pk_mul_f32 v[190:191], v[120:121], v[238:239]
	v_pk_fma_f32 v[188:189], v[118:119], v[240:241], v[188:189]
	v_pk_fma_f32 v[190:191], v[122:123], v[240:241], v[190:191]
	v_add_f32_e32 v246, v188, v189
	v_add_f32_e32 v247, v190, v191
	ds_write_b64 v159, v[246:247] offset:58368
	ds_read_b128 v[192:195], v124 offset:52224
	ds_read_b128 v[196:199], v124 offset:52240
	s_mul_i32 s20, s26, -9
	s_add_i32 s20, s20, 12
	s_add_i32 s20, s20, s27
	s_waitcnt lgkmcnt(0)
	v_pk_add_f32 v[192:193], v[192:193], v[194:195]
	v_pk_add_f32 v[196:197], v[196:197], v[198:199]
	s_add_i32 s20, s20, s100
	v_pk_add_f32 v[192:193], v[192:193], v[196:197]
	s_mulk_i32 s20, 0x600
	s_nop 0
	v_add_f32_dpp v192, v192, v192 quad_perm:[1,0,3,2] row_mask:0xf bank_mask:0xf bound_ctrl:1
	v_add_f32_dpp v193, v193, v193 quad_perm:[1,0,3,2] row_mask:0xf bank_mask:0xf bound_ctrl:1
	v_add_u32_e32 v125, s20, v200
	v_add_f32_dpp v192, v192, v192 quad_perm:[2,3,0,1] row_mask:0xf bank_mask:0xf bound_ctrl:1
	v_add_f32_dpp v193, v193, v193 quad_perm:[2,3,0,1] row_mask:0xf bank_mask:0xf bound_ctrl:1
	global_store_dwordx2 v125, v[192:193], s[98:99]
	s_barrier
	v_subrev_u32_e32 v100, s101, v100
	v_subrev_u32_e32 v97, s101, v97
	s_sub_i32 s101, 0, s101
	s_mov_b32 s100, s29
	s_mov_b32 s29, s28
	s_add_i32 s38, s38, 1
	s_cmpk_lg_i32 s38, 0x90
	s_cbranch_scc1 .Lscan_loop
	v_readlane_b32 s49, v250, 7
	s_nop 3
	s_branch .Lscan_joins_queue
